# spatial-gating statistics pass: loads of batches 1 and 2 issued with batch 0 into two fresh register banks, batch 3 loaded during batch 2 (one exposed HBM latency instead of four)
# speedup vs baseline: 1.0045x; 1.0045x over previous
; DI float bf_lo(unsigned u) { return __uint_as_float(u << 16); }
; DI float bf_hi(unsigned u) { return __uint_as_float(u & 0xffff0000u); }
; DI void sg_phase(const Params& p, lds_t* shm) {
;     ...
;     for (int t4 = 0; t4 < 16; t4 += 4) {
;       u32x4 rv[4][2];
; #pragma unroll
;       for (int q = 0; q < 4; ++q) { const u32x4* rp = (const u32x4*)(Vs + (size_t)(w * 128 + wid * 16 + t4 + q) * DM); rv[q][0] = rp[lane]; rv[q][1] = rp[lane + 64]; }
;       float sm[4], sq[4];
; #pragma unroll
;       for (int q = 0; q < 4; ++q) { float a0 = 0.f, a1 = 0.f;
; #pragma unroll
;         for (int i = 0; i < 2; ++i)
; #pragma unroll
;           for (int e = 0; e < 4; ++e) { const float a = bf_lo(rv[q][i][e]), bb = bf_hi(rv[q][i][e]); a0 += a + bb; a1 += a * a + bb * bb; }
;         sm[q] = a0; sq[q] = a1; }
.LBB0_387:
	s_lshl_b32 s8, s3, 7
	v_add_u32_e32 v8, s8, v70
	v_ashrrev_i32_e32 v9, 31, v8
	v_lshlrev_b64 v[0:1], 11, v[8:9]
	v_lshl_add_u64 v[0:1], v[50:51], 0, v[0:1]
	s_barrier
	global_load_dwordx4 v[10:13], v[0:1], off
	global_load_dwordx4 v[14:17], v[0:1], off offset:1024
	v_or_b32_e32 v0, 1, v8
	v_ashrrev_i32_e32 v1, 31, v0
	v_lshlrev_b64 v[0:1], 11, v[0:1]
	v_lshl_add_u64 v[0:1], v[50:51], 0, v[0:1]
	global_load_dwordx4 v[18:21], v[0:1], off
	global_load_dwordx4 v[22:25], v[0:1], off offset:1024
	v_or_b32_e32 v2, 2, v8
	v_or_b32_e32 v0, 3, v8
	v_ashrrev_i32_e32 v3, 31, v2
	v_ashrrev_i32_e32 v1, 31, v0
	v_lshlrev_b64 v[2:3], 11, v[2:3]
	v_lshlrev_b64 v[0:1], 11, v[0:1]
	v_lshl_add_u64 v[2:3], v[50:51], 0, v[2:3]
	v_lshl_add_u64 v[0:1], v[50:51], 0, v[0:1]
	global_load_dwordx4 v[26:29], v[2:3], off
	global_load_dwordx4 v[30:33], v[2:3], off offset:1024
	global_load_dwordx4 v[4:7], v[0:1], off
	s_nop 0
	global_load_dwordx4 v[0:3], v[0:1], off offset:1024
	v_or_b32_e32 v230, 4, v8
	v_ashrrev_i32_e32 v231, 31, v230
	v_lshlrev_b64 v[230:231], 11, v[230:231]
	v_lshl_add_u64 v[230:231], v[50:51], 0, v[230:231]
	global_load_dwordx4 v[160:163], v[230:231], off
	global_load_dwordx4 v[164:167], v[230:231], off offset:1024
	v_or_b32_e32 v230, 5, v8
	v_ashrrev_i32_e32 v231, 31, v230
	v_lshlrev_b64 v[230:231], 11, v[230:231]
	v_lshl_add_u64 v[230:231], v[50:51], 0, v[230:231]
	global_load_dwordx4 v[168:171], v[230:231], off
	global_load_dwordx4 v[172:175], v[230:231], off offset:1024
	v_or_b32_e32 v230, 6, v8
	v_ashrrev_i32_e32 v231, 31, v230
	v_lshlrev_b64 v[230:231], 11, v[230:231]
	v_lshl_add_u64 v[230:231], v[50:51], 0, v[230:231]
	global_load_dwordx4 v[176:179], v[230:231], off
	global_load_dwordx4 v[180:183], v[230:231], off offset:1024
	v_or_b32_e32 v230, 7, v8
	v_ashrrev_i32_e32 v231, 31, v230
	v_lshlrev_b64 v[230:231], 11, v[230:231]
	v_lshl_add_u64 v[230:231], v[50:51], 0, v[230:231]
	global_load_dwordx4 v[184:187], v[230:231], off
	global_load_dwordx4 v[188:191], v[230:231], off offset:1024
	v_or_b32_e32 v230, 8, v8
	v_ashrrev_i32_e32 v231, 31, v230
	v_lshlrev_b64 v[230:231], 11, v[230:231]
	v_lshl_add_u64 v[230:231], v[50:51], 0, v[230:231]
	global_load_dwordx4 v[192:195], v[230:231], off
	global_load_dwordx4 v[196:199], v[230:231], off offset:1024
	v_or_b32_e32 v230, 9, v8
	v_ashrrev_i32_e32 v231, 31, v230
	v_lshlrev_b64 v[230:231], 11, v[230:231]
	v_lshl_add_u64 v[230:231], v[50:51], 0, v[230:231]
	global_load_dwordx4 v[200:203], v[230:231], off
	global_load_dwordx4 v[204:207], v[230:231], off offset:1024
	v_or_b32_e32 v230, 10, v8
	v_ashrrev_i32_e32 v231, 31, v230
	v_lshlrev_b64 v[230:231], 11, v[230:231]
	v_lshl_add_u64 v[230:231], v[50:51], 0, v[230:231]
	global_load_dwordx4 v[208:211], v[230:231], off
	global_load_dwordx4 v[218:221], v[230:231], off offset:1024
	v_or_b32_e32 v230, 11, v8
	v_ashrrev_i32_e32 v231, 31, v230
	v_lshlrev_b64 v[230:231], 11, v[230:231]
	v_lshl_add_u64 v[230:231], v[50:51], 0, v[230:231]
	global_load_dwordx4 v[222:225], v[230:231], off
	global_load_dwordx4 v[226:229], v[230:231], off offset:1024
	s_waitcnt vmcnt(23)
	v_and_b32_e32 v35, 0xffff0000, v11
	v_lshlrev_b32_e32 v11, 16, v11
	v_and_b32_e32 v9, 0xffff0000, v10
	v_lshlrev_b32_e32 v37, 16, v12
	v_and_b32_e32 v39, 0xffff0000, v12
	v_lshlrev_b32_e32 v10, 16, v10
	v_lshlrev_b32_e32 v41, 16, v13
	v_and_b32_e32 v13, 0xffff0000, v13
	v_mov_b32_e32 v66, v11
	s_waitcnt vmcnt(21)
	v_and_b32_e32 v67, 0xffff0000, v19
	v_lshlrev_b32_e32 v19, 16, v19
	v_mul_f32_e32 v36, v37, v37
	v_mul_f32_e32 v38, v39, v39
	v_mul_f32_e32 v64, v10, v10
	v_mov_b32_e32 v65, v11
	v_mul_f32_e32 v34, v9, v9
	v_pk_add_f32 v[68:69], v[10:11], v[8:9] op_sel:[1,0] op_sel_hi:[0,1]
	v_mul_f32_e32 v40, v41, v41
	v_mul_f32_e32 v12, v13, v13
	v_and_b32_e32 v9, 0xffff0000, v18
	v_lshlrev_b32_e32 v101, 16, v20
	v_and_b32_e32 v103, 0xffff0000, v20
	v_lshlrev_b32_e32 v18, 16, v18
	v_lshlrev_b32_e32 v105, 16, v21
	v_and_b32_e32 v21, 0xffff0000, v21
	v_pk_mul_f32 v[10:11], v[10:11], v[66:67] op_sel:[1,0] op_sel_hi:[0,1]
	v_mov_b32_e32 v20, v19
	v_mul_f32_e32 v48, v35, v35
	v_pk_add_f32 v[36:37], v[36:37], v[38:39]
	v_pk_add_f32 v[12:13], v[40:41], v[12:13]
	v_mul_f32_e32 v100, v101, v101
	v_mul_f32_e32 v102, v103, v103
	v_mul_f32_e32 v38, v18, v18
	v_mov_b32_e32 v39, v19
	v_mul_f32_e32 v66, v9, v9
	v_pk_add_f32 v[40:41], v[18:19], v[8:9] op_sel:[1,0] op_sel_hi:[0,1]
	v_mov_b32_e32 v11, v69
	v_pk_mul_f32 v[18:19], v[18:19], v[20:21] op_sel:[1,0] op_sel_hi:[0,1]
	v_mul_f32_e32 v104, v105, v105
	v_mul_f32_e32 v20, v21, v21
	s_waitcnt vmcnt(19)
	v_and_b32_e32 v9, 0xffff0000, v26
	v_and_b32_e32 v69, 0xffff0000, v27
	v_lshlrev_b32_e32 v27, 16, v27
	v_lshlrev_b32_e32 v26, 16, v26
	v_pk_add_f32 v[34:35], v[64:65], v[34:35]
	v_pk_add_f32 v[64:65], v[100:101], v[102:103]
	v_pk_add_f32 v[10:11], v[10:11], v[48:49]
	v_mul_f32_e32 v48, v67, v67
	v_mov_b32_e32 v19, v41
	v_pk_add_f32 v[20:21], v[104:105], v[20:21]
	v_lshlrev_b32_e32 v101, 16, v28
	v_and_b32_e32 v103, 0xffff0000, v28
	v_mul_f32_e32 v104, v26, v26
	v_mov_b32_e32 v28, v27
	v_mov_b32_e32 v105, v27
	v_mul_f32_e32 v68, v9, v9
	v_pk_add_f32 v[18:19], v[18:19], v[48:49]
	v_mul_f32_e32 v48, v69, v69
	v_pk_add_f32 v[68:69], v[104:105], v[68:69]
	v_pk_mul_f32 v[104:105], v[26:27], v[28:29] op_sel:[1,0] op_sel_hi:[0,1]
	v_pk_add_f32 v[26:27], v[26:27], v[8:9] op_sel:[1,0] op_sel_hi:[0,1]
	s_waitcnt vmcnt(17)
; DI float bf_lo(unsigned u) { return __uint_as_float(u << 16); }
; DI float bf_hi(unsigned u) { return __uint_as_float(u & 0xffff0000u); }
; DI void sg_phase(const Params& p, lds_t* shm) {
;     ...
;       for (int q = 0; q < 4; ++q) { const u32x4* rp = (const u32x4*)(Vs + (size_t)(w * 128 + wid * 16 + t4 + q) * DM); rv[q][0] = rp[lane]; rv[q][1] = rp[lane + 64]; }
;       float sm[4], sq[4];
; #pragma unroll
;       for (int q = 0; q < 4; ++q) { float a0 = 0.f, a1 = 0.f;
; #pragma unroll
;         for (int i = 0; i < 2; ++i)
; #pragma unroll
;           for (int e = 0; e < 4; ++e) { const float a = bf_lo(rv[q][i][e]), bb = bf_hi(rv[q][i][e]); a0 += a + bb; a1 += a * a + bb * bb; }
;         sm[q] = a0; sq[q] = a1; }
; #pragma unroll
;       for (int q = 0; q < 4; ++q) { sm[q] = wave_sum(sm[q]); sq[q] = wave_sum(sq[q]); }
	v_and_b32_e32 v9, 0xffff0000, v4
	v_and_b32_e32 v111, 0xffff0000, v5
	v_lshlrev_b32_e32 v5, 16, v5
	v_lshlrev_b32_e32 v4, 16, v4
	v_mov_b32_e32 v105, v27
	v_lshlrev_b32_e32 v113, 16, v6
	v_and_b32_e32 v115, 0xffff0000, v6
	v_mul_f32_e32 v116, v4, v4
	v_mov_b32_e32 v6, v5
	v_mov_b32_e32 v117, v5
	v_mul_f32_e32 v110, v9, v9
	v_pk_add_f32 v[26:27], v[104:105], v[48:49]
	v_mul_f32_e32 v48, v111, v111
	v_pk_add_f32 v[110:111], v[116:117], v[110:111]
	v_pk_mul_f32 v[116:117], v[4:5], v[6:7] op_sel:[1,0] op_sel_hi:[0,1]
	v_pk_add_f32 v[4:5], v[4:5], v[8:9] op_sel:[1,0] op_sel_hi:[0,1]
	v_mov_b32_e32 v117, v5
	v_mul_f32_e32 v112, v113, v113
	v_mul_f32_e32 v114, v115, v115
	v_pk_add_f32 v[4:5], v[116:117], v[48:49]
	v_lshlrev_b32_e32 v43, 16, v14
	v_pk_add_f32 v[4:5], v[110:111], v[4:5]
	v_pk_add_f32 v[110:111], v[112:113], v[114:115]
	v_and_b32_e32 v45, 0xffff0000, v14
	v_pk_add_f32 v[10:11], v[34:35], v[10:11]
	v_pk_add_f32 v[4:5], v[110:111], v[4:5]
	v_lshlrev_b32_e32 v111, 16, v7
	v_and_b32_e32 v7, 0xffff0000, v7
	v_lshlrev_b32_e32 v47, 16, v15
	v_and_b32_e32 v15, 0xffff0000, v15
	v_mul_f32_e32 v42, v43, v43
	v_mul_f32_e32 v44, v45, v45
	v_pk_add_f32 v[10:11], v[36:37], v[10:11]
	v_mul_f32_e32 v110, v111, v111
	v_mul_f32_e32 v6, v7, v7
	v_lshlrev_b32_e32 v59, 16, v16
	v_and_b32_e32 v61, 0xffff0000, v16
	v_mul_f32_e32 v46, v47, v47
	v_mul_f32_e32 v14, v15, v15
	v_pk_add_f32 v[6:7], v[110:111], v[6:7]
	s_waitcnt vmcnt(16)
	v_lshlrev_b32_e32 v111, 16, v0
	v_and_b32_e32 v113, 0xffff0000, v0
	v_lshlrev_b32_e32 v115, 16, v1
	v_and_b32_e32 v117, 0xffff0000, v1
	v_pk_add_f32 v[0:1], v[12:13], v[10:11]
	v_pk_add_f32 v[10:11], v[42:43], v[44:45]
	v_lshlrev_b32_e32 v63, 16, v17
	v_and_b32_e32 v17, 0xffff0000, v17
	v_mul_f32_e32 v58, v59, v59
	v_mul_f32_e32 v60, v61, v61
	v_pk_add_f32 v[0:1], v[10:11], v[0:1]
	v_pk_add_f32 v[10:11], v[46:47], v[14:15]
	v_mul_f32_e32 v62, v63, v63
	v_mul_f32_e32 v16, v17, v17
	v_pk_add_f32 v[0:1], v[10:11], v[0:1]
	v_pk_add_f32 v[10:11], v[58:59], v[60:61]
	v_pk_add_f32 v[38:39], v[38:39], v[66:67]
	v_pk_add_f32 v[0:1], v[10:11], v[0:1]
	v_pk_add_f32 v[10:11], v[62:63], v[16:17]
	v_pk_add_f32 v[18:19], v[38:39], v[18:19]
	v_lshlrev_b32_e32 v35, 16, v22
	v_and_b32_e32 v37, 0xffff0000, v22
	v_pk_add_f32 v[0:1], v[10:11], v[0:1]
	v_pk_add_f32 v[18:19], v[64:65], v[18:19]
	v_mul_f32_e32 v34, v35, v35
	v_mul_f32_e32 v36, v37, v37
	v_lshlrev_b32_e32 v39, 16, v23
	v_and_b32_e32 v23, 0xffff0000, v23
	ds_bpermute_b32 v11, v71, v1
	ds_bpermute_b32 v10, v71, v0
	v_mul_f32_e32 v38, v39, v39
	v_mul_f32_e32 v22, v23, v23
	v_lshlrev_b32_e32 v41, 16, v24
	v_and_b32_e32 v65, 0xffff0000, v24
	v_pk_add_f32 v[16:17], v[20:21], v[18:19]
	v_pk_add_f32 v[18:19], v[34:35], v[36:37]
	v_mul_f32_e32 v40, v41, v41
	v_mul_f32_e32 v64, v65, v65
	v_lshlrev_b32_e32 v67, 16, v25
	v_and_b32_e32 v25, 0xffff0000, v25
	v_pk_add_f32 v[16:17], v[18:19], v[16:17]
	v_pk_add_f32 v[18:19], v[38:39], v[22:23]
	v_mul_f32_e32 v66, v67, v67
	v_mul_f32_e32 v24, v25, v25
	v_pk_add_f32 v[16:17], v[18:19], v[16:17]
	v_pk_add_f32 v[18:19], v[40:41], v[64:65]
	s_waitcnt lgkmcnt(0)
	v_pk_add_f32 v[0:1], v[0:1], v[10:11]
	v_pk_add_f32 v[16:17], v[18:19], v[16:17]
	v_pk_add_f32 v[18:19], v[66:67], v[24:25]
	ds_bpermute_b32 v11, v72, v1
	v_pk_add_f32 v[16:17], v[18:19], v[16:17]
	ds_bpermute_b32 v10, v72, v0
	ds_bpermute_b32 v19, v71, v17
	ds_bpermute_b32 v18, v71, v16
	v_mul_f32_e32 v100, v101, v101
	v_mul_f32_e32 v102, v103, v103
	s_waitcnt lgkmcnt(2)
	v_pk_add_f32 v[0:1], v[0:1], v[10:11]
	ds_bpermute_b32 v11, v73, v1
	s_waitcnt lgkmcnt(1)
	v_pk_add_f32 v[16:17], v[16:17], v[18:19]
	ds_bpermute_b32 v10, v73, v0
	ds_bpermute_b32 v19, v72, v17
	ds_bpermute_b32 v18, v72, v16
	v_pk_add_f32 v[26:27], v[68:69], v[26:27]
	v_pk_add_f32 v[68:69], v[100:101], v[102:103]
	s_waitcnt lgkmcnt(2)
	v_pk_add_f32 v[0:1], v[0:1], v[10:11]
	v_pk_add_f32 v[26:27], v[68:69], v[26:27]
	s_waitcnt lgkmcnt(0)
	v_pk_add_f32 v[10:11], v[16:17], v[18:19]
	ds_bpermute_b32 v17, v73, v11
	ds_bpermute_b32 v16, v73, v10
	v_lshlrev_b32_e32 v69, 16, v29
	v_and_b32_e32 v29, 0xffff0000, v29
	v_mul_f32_e32 v68, v69, v69
	v_mul_f32_e32 v28, v29, v29
	s_waitcnt lgkmcnt(0)
	v_pk_add_f32 v[10:11], v[10:11], v[16:17]
	ds_bpermute_b32 v17, v74, v11
	ds_bpermute_b32 v16, v74, v10
	v_pk_add_f32 v[28:29], v[68:69], v[28:29]
	v_lshlrev_b32_e32 v69, 16, v30
	v_and_b32_e32 v101, 0xffff0000, v30
	v_mul_f32_e32 v68, v69, v69
	v_mul_f32_e32 v100, v101, v101
	v_lshlrev_b32_e32 v103, 16, v31
	v_and_b32_e32 v31, 0xffff0000, v31
	v_mul_f32_e32 v110, v111, v111
	v_mul_f32_e32 v112, v113, v113
	v_mul_f32_e32 v102, v103, v103
	v_mul_f32_e32 v30, v31, v31
	v_lshlrev_b32_e32 v105, 16, v32
	v_and_b32_e32 v107, 0xffff0000, v32
	v_mul_f32_e32 v114, v115, v115
	v_mul_f32_e32 v116, v117, v117
	v_lshlrev_b32_e32 v13, 16, v2
	v_and_b32_e32 v15, 0xffff0000, v2
	s_waitcnt lgkmcnt(0)
	v_pk_add_f32 v[10:11], v[10:11], v[16:17]
	v_pk_add_f32 v[16:17], v[28:29], v[26:27]
	v_pk_add_f32 v[18:19], v[68:69], v[100:101]
	v_pk_add_f32 v[4:5], v[6:7], v[4:5]
	v_pk_add_f32 v[6:7], v[110:111], v[112:113]
	v_mul_f32_e32 v104, v105, v105
	v_mul_f32_e32 v106, v107, v107
	v_lshlrev_b32_e32 v109, 16, v33
	v_and_b32_e32 v33, 0xffff0000, v33
	v_mul_f32_e32 v12, v13, v13
	v_mul_f32_e32 v14, v15, v15
	v_lshlrev_b32_e32 v21, 16, v3
	v_and_b32_e32 v23, 0xffff0000, v3
	v_pk_add_f32 v[16:17], v[18:19], v[16:17]
	v_pk_add_f32 v[18:19], v[102:103], v[30:31]
	v_pk_add_f32 v[4:5], v[6:7], v[4:5]
	v_pk_add_f32 v[6:7], v[114:115], v[116:117]
	v_mul_f32_e32 v108, v109, v109
	v_mul_f32_e32 v32, v33, v33
	v_mul_f32_e32 v20, v21, v21
	v_mul_f32_e32 v22, v23, v23
	v_pk_add_f32 v[16:17], v[18:19], v[16:17]
	v_pk_add_f32 v[18:19], v[104:105], v[106:107]
	v_pk_add_f32 v[4:5], v[6:7], v[4:5]
	v_pk_add_f32 v[6:7], v[12:13], v[14:15]
	v_pk_add_f32 v[16:17], v[18:19], v[16:17]
	v_pk_add_f32 v[18:19], v[108:109], v[32:33]
	v_pk_add_f32 v[4:5], v[6:7], v[4:5]
	v_pk_add_f32 v[6:7], v[20:21], v[22:23]
	v_pk_add_f32 v[16:17], v[18:19], v[16:17]
	v_pk_add_f32 v[4:5], v[6:7], v[4:5]
	ds_bpermute_b32 v19, v71, v17
	ds_bpermute_b32 v18, v71, v16
	ds_bpermute_b32 v7, v71, v5
	ds_bpermute_b32 v6, v71, v4
	ds_bpermute_b32 v13, v75, v11
	ds_bpermute_b32 v12, v75, v10
	s_waitcnt lgkmcnt(4)
; DI float bf_lo(unsigned u) { return __uint_as_float(u << 16); }
; DI float bf_hi(unsigned u) { return __uint_as_float(u & 0xffff0000u); }
; DI void sg_phase(const Params& p, lds_t* shm) {
;     ...
;     for (int t4 = 0; t4 < 16; t4 += 4) {
;       u32x4 rv[4][2];
; #pragma unroll
;       for (int q = 0; q < 4; ++q) { const u32x4* rp = (const u32x4*)(Vs + (size_t)(w * 128 + wid * 16 + t4 + q) * DM); rv[q][0] = rp[lane]; rv[q][1] = rp[lane + 64]; }
;       float sm[4], sq[4];
; #pragma unroll
;       for (int q = 0; q < 4; ++q) { float a0 = 0.f, a1 = 0.f;
; #pragma unroll
;         for (int i = 0; i < 2; ++i)
; #pragma unroll
;           for (int e = 0; e < 4; ++e) { const float a = bf_lo(rv[q][i][e]), bb = bf_hi(rv[q][i][e]); a0 += a + bb; a1 += a * a + bb * bb; }
;         sm[q] = a0; sq[q] = a1; }
;     ...
;       for (int q = 0; q < 4; ++q) { sm[q] = wave_sum(sm[q]); sq[q] = wave_sum(sq[q]); }
; #pragma unroll
;       for (int q = 0; q < 4; ++q) { const int j = wid * 16 + t4 + q; const float mu = sm[q] * (1.0f / DM), var = fmaxf(sq[q] * (1.0f / DM) - mu * mu, 0.f);
;         if (lane == 0) { stats[2 * j] = mu; stats[2 * j + 1] = rsqrtf(var + 1e-5f); } }
	v_pk_add_f32 v[14:15], v[16:17], v[18:19]
	ds_bpermute_b32 v17, v72, v15
	s_waitcnt lgkmcnt(3)
	v_pk_add_f32 v[4:5], v[4:5], v[6:7]
	ds_bpermute_b32 v16, v72, v14
	ds_bpermute_b32 v7, v72, v5
	ds_bpermute_b32 v6, v72, v4
	s_waitcnt lgkmcnt(4)
	v_pk_add_f32 v[12:13], v[10:11], v[12:13]
	ds_bpermute_b32 v3, v74, v1
	s_waitcnt lgkmcnt(3)
	v_pk_add_f32 v[14:15], v[14:15], v[16:17]
	ds_bpermute_b32 v17, v73, v15
	s_waitcnt lgkmcnt(2)
	v_pk_add_f32 v[4:5], v[4:5], v[6:7]
	ds_bpermute_b32 v16, v73, v14
	ds_bpermute_b32 v7, v73, v5
	ds_bpermute_b32 v6, v73, v4
	ds_bpermute_b32 v2, v74, v0
	s_waitcnt lgkmcnt(3)
	v_pk_add_f32 v[10:11], v[14:15], v[16:17]
	ds_bpermute_b32 v15, v74, v11
	s_waitcnt lgkmcnt(2)
	v_pk_add_f32 v[4:5], v[4:5], v[6:7]
	ds_bpermute_b32 v14, v74, v10
	ds_bpermute_b32 v7, v74, v5
	ds_bpermute_b32 v6, v74, v4
	s_waitcnt lgkmcnt(4)
	v_pk_add_f32 v[0:1], v[0:1], v[2:3]
	ds_bpermute_b32 v3, v75, v1
	s_waitcnt lgkmcnt(3)
	v_pk_add_f32 v[10:11], v[10:11], v[14:15]
	ds_bpermute_b32 v2, v75, v0
	s_waitcnt lgkmcnt(2)
	v_pk_add_f32 v[4:5], v[4:5], v[6:7]
	ds_bpermute_b32 v15, v75, v11
	ds_bpermute_b32 v14, v75, v10
	ds_bpermute_b32 v7, v75, v5
	ds_bpermute_b32 v6, v75, v4
	s_waitcnt lgkmcnt(4)
	v_pk_add_f32 v[0:1], v[0:1], v[2:3]
	ds_bpermute_b32 v3, v76, v1
	s_waitcnt lgkmcnt(3)
	v_pk_add_f32 v[10:11], v[10:11], v[14:15]
	ds_bpermute_b32 v2, v76, v0
	s_waitcnt lgkmcnt(2)
	v_pk_add_f32 v[4:5], v[4:5], v[6:7]
	ds_bpermute_b32 v17, v76, v13
	ds_bpermute_b32 v16, v76, v12
	ds_bpermute_b32 v15, v76, v11
	ds_bpermute_b32 v14, v76, v10
	ds_bpermute_b32 v7, v76, v5
	ds_bpermute_b32 v6, v76, v4
	s_and_saveexec_b64 s[0:1], vcc
	s_cbranch_execz .LBB0_389
	s_waitcnt lgkmcnt(6)
	v_pk_add_f32 v[0:1], v[0:1], v[2:3]
	s_waitcnt lgkmcnt(2)
	v_pk_add_f32 v[10:11], v[10:11], v[14:15]
	v_pk_mul_f32 v[18:19], v[0:1], s[10:11] op_sel_hi:[1,0]
	v_pk_mul_f32 v[10:11], v[10:11], s[10:11] op_sel_hi:[1,0]
	v_fma_f32 v0, -v19, v19, v18
	v_max_f32_e32 v0, 0, v0
	v_add_f32_e32 v0, 0x3727c5ac, v0
	v_mul_f32_e32 v1, 0x4b800000, v0
	v_cmp_gt_f32_e64 s[4:5], s2, v0
	s_waitcnt lgkmcnt(0)
	v_pk_add_f32 v[4:5], v[4:5], v[6:7]
	v_fma_f32 v9, -v11, v11, v10
	v_cndmask_b32_e64 v0, v0, v1, s[4:5]
	v_rsq_f32_e32 v2, v0
	v_pk_add_f32 v[0:1], v[12:13], v[16:17]
	v_pk_mul_f32 v[4:5], v[4:5], s[10:11] op_sel_hi:[1,0]
	v_pk_mul_f32 v[12:13], v[0:1], s[10:11] op_sel_hi:[1,0]
	v_max_f32_e32 v9, 0, v9
	v_fma_f32 v0, -v13, v13, v12
	v_max_f32_e32 v0, 0, v0
	v_add_f32_e32 v0, 0x3727c5ac, v0
	v_mul_f32_e32 v1, 0x4b800000, v0
	v_cmp_gt_f32_e64 s[6:7], s2, v0
	v_fma_f32 v4, -v5, v5, v4
	v_add_f32_e32 v9, 0x3727c5ac, v9
	v_cndmask_b32_e64 v0, v0, v1, s[6:7]
	v_rsq_f32_e32 v0, v0
	v_mul_f32_e32 v1, 0x45800000, v2
	v_max_f32_e32 v4, 0, v4
	v_cndmask_b32_e64 v1, v2, v1, s[4:5]
	v_mul_f32_e32 v2, 0x45800000, v0
	v_mul_f32_e32 v10, 0x4b800000, v9
	v_cmp_gt_f32_e64 s[4:5], s2, v9
	v_add_f32_e32 v4, 0x3727c5ac, v4
	v_cndmask_b32_e64 v3, v0, v2, s[6:7]
	v_cndmask_b32_e64 v9, v9, v10, s[4:5]
	v_mul_f32_e32 v6, 0x4b800000, v4
	v_cmp_gt_f32_e64 s[6:7], s2, v4
	v_rsq_f32_e32 v9, v9
	v_mov_b32_e32 v0, v19
	v_cndmask_b32_e64 v4, v4, v6, s[6:7]
	v_rsq_f32_e32 v4, v4
	v_mov_b32_e32 v2, v13
	ds_write_b128 v99, v[0:3] offset:32768
	v_mul_f32_e32 v0, 0x45800000, v9
	v_cndmask_b32_e64 v1, v9, v0, s[4:5]
	v_mul_f32_e32 v0, 0x45800000, v4
	v_cndmask_b32_e64 v3, v4, v0, s[6:7]
	v_mov_b32_e32 v0, v11
	v_mov_b32_e32 v2, v5
	ds_write_b128 v99, v[0:3] offset:32784
.LBB0_389:
	s_or_b64 exec, exec, s[0:1]
	s_waitcnt lgkmcnt(2)
	s_waitcnt lgkmcnt(0)
	s_nop 0
	s_waitcnt vmcnt(15)
	v_and_b32_e32 v9, 0xffff0000, v160
	v_and_b32_e32 v35, 0xffff0000, v161
	v_lshlrev_b32_e32 v11, 16, v161
	v_lshlrev_b32_e32 v10, 16, v160
	v_lshlrev_b32_e32 v41, 16, v163
	v_and_b32_e32 v13, 0xffff0000, v163
	s_waitcnt vmcnt(13)
	v_and_b32_e32 v65, 0xffff0000, v168
	v_and_b32_e32 v67, 0xffff0000, v169
	v_lshlrev_b32_e32 v69, 16, v170
	v_and_b32_e32 v101, 0xffff0000, v170
	v_lshlrev_b32_e32 v19, 16, v169
	v_mov_b32_e32 v64, v11
	v_pk_add_f32 v[106:107], v[10:11], v[8:9] op_sel:[1,0] op_sel_hi:[0,1]
	v_lshlrev_b32_e32 v37, 16, v162
	v_and_b32_e32 v39, 0xffff0000, v162
	v_lshlrev_b32_e32 v18, 16, v168
	v_lshlrev_b32_e32 v103, 16, v171
	v_and_b32_e32 v21, 0xffff0000, v171
	v_mul_f32_e32 v104, v10, v10
	v_mov_b32_e32 v105, v11
	v_mul_f32_e32 v40, v41, v41
	v_mul_f32_e32 v12, v13, v13
	v_mul_f32_e32 v68, v69, v69
	v_mul_f32_e32 v100, v101, v101
	v_mov_b32_e32 v106, v19
	v_pk_mul_f32 v[10:11], v[10:11], v[64:65] op_sel:[1,0] op_sel_hi:[0,1]
	v_mul_f32_e32 v48, v35, v35
	v_mul_f32_e32 v34, v9, v9
	v_mul_f32_e32 v108, v18, v18
	v_mov_b32_e32 v109, v19
	v_pk_add_f32 v[110:111], v[18:19], v[64:65] op_sel:[1,0] op_sel_hi:[0,1]
	v_mul_f32_e32 v102, v103, v103
	v_mul_f32_e32 v20, v21, v21
	v_pk_add_f32 v[12:13], v[40:41], v[12:13]
	v_pk_mul_f32 v[18:19], v[18:19], v[106:107] op_sel:[1,0] op_sel_hi:[0,1]
	v_pk_add_f32 v[40:41], v[68:69], v[100:101]
	v_mov_b32_e32 v11, v107
	s_waitcnt vmcnt(11)
	v_and_b32_e32 v9, 0xffff0000, v176
	v_and_b32_e32 v69, 0xffff0000, v177
	v_lshlrev_b32_e32 v27, 16, v177
	v_lshlrev_b32_e32 v26, 16, v176
	v_pk_add_f32 v[34:35], v[104:105], v[34:35]
	v_pk_add_f32 v[20:21], v[102:103], v[20:21]
	v_mov_b32_e32 v19, v111
	v_pk_add_f32 v[10:11], v[10:11], v[48:49]
	v_mul_f32_e32 v48, v67, v67
	v_lshlrev_b32_e32 v101, 16, v178
	v_and_b32_e32 v103, 0xffff0000, v178
	v_mul_f32_e32 v104, v26, v26
	v_mov_b32_e32 v28, v27
	v_mov_b32_e32 v105, v27
	v_mul_f32_e32 v68, v9, v9
	v_pk_add_f32 v[18:19], v[18:19], v[48:49]
	v_mul_f32_e32 v48, v69, v69
	v_pk_add_f32 v[68:69], v[104:105], v[68:69]
	v_mov_b32_e32 v29, v179
	v_pk_mul_f32 v[104:105], v[26:27], v[28:29] op_sel:[1,0] op_sel_hi:[0,1]
	v_pk_add_f32 v[26:27], v[26:27], v[8:9] op_sel:[1,0] op_sel_hi:[0,1]
	s_waitcnt vmcnt(9)
; DI float bf_lo(unsigned u) { return __uint_as_float(u << 16); }
; DI float bf_hi(unsigned u) { return __uint_as_float(u & 0xffff0000u); }
; DI void sg_phase(const Params& p, lds_t* shm) {
;     ...
;       for (int q = 0; q < 4; ++q) { const u32x4* rp = (const u32x4*)(Vs + (size_t)(w * 128 + wid * 16 + t4 + q) * DM); rv[q][0] = rp[lane]; rv[q][1] = rp[lane + 64]; }
;       float sm[4], sq[4];
; #pragma unroll
;       for (int q = 0; q < 4; ++q) { float a0 = 0.f, a1 = 0.f;
; #pragma unroll
;         for (int i = 0; i < 2; ++i)
; #pragma unroll
;           for (int e = 0; e < 4; ++e) { const float a = bf_lo(rv[q][i][e]), bb = bf_hi(rv[q][i][e]); a0 += a + bb; a1 += a * a + bb * bb; }
;         sm[q] = a0; sq[q] = a1; }
; #pragma unroll
;       for (int q = 0; q < 4; ++q) { sm[q] = wave_sum(sm[q]); sq[q] = wave_sum(sq[q]); }
	v_and_b32_e32 v9, 0xffff0000, v184
	v_and_b32_e32 v111, 0xffff0000, v185
	v_lshlrev_b32_e32 v5, 16, v185
	v_lshlrev_b32_e32 v4, 16, v184
	v_mov_b32_e32 v105, v27
	v_lshlrev_b32_e32 v113, 16, v186
	v_and_b32_e32 v115, 0xffff0000, v186
	v_mul_f32_e32 v116, v4, v4
	v_mov_b32_e32 v6, v5
	v_mov_b32_e32 v117, v5
	v_mul_f32_e32 v110, v9, v9
	v_pk_add_f32 v[26:27], v[104:105], v[48:49]
	v_mul_f32_e32 v48, v111, v111
	v_pk_add_f32 v[110:111], v[116:117], v[110:111]
	v_mov_b32_e32 v7, v187
	v_pk_mul_f32 v[116:117], v[4:5], v[6:7] op_sel:[1,0] op_sel_hi:[0,1]
	v_pk_add_f32 v[4:5], v[4:5], v[8:9] op_sel:[1,0] op_sel_hi:[0,1]
	v_mov_b32_e32 v117, v5
	v_mul_f32_e32 v112, v113, v113
	v_mul_f32_e32 v114, v115, v115
	v_pk_add_f32 v[4:5], v[116:117], v[48:49]
	v_mul_f32_e32 v36, v37, v37
	v_mul_f32_e32 v38, v39, v39
	v_pk_add_f32 v[4:5], v[110:111], v[4:5]
	v_pk_add_f32 v[110:111], v[112:113], v[114:115]
	v_lshlrev_b32_e32 v43, 16, v164
	v_and_b32_e32 v45, 0xffff0000, v164
	v_pk_add_f32 v[36:37], v[36:37], v[38:39]
	v_pk_add_f32 v[10:11], v[34:35], v[10:11]
	v_pk_add_f32 v[4:5], v[110:111], v[4:5]
	v_lshlrev_b32_e32 v111, 16, v7
	v_and_b32_e32 v7, 0xffff0000, v7
	v_lshlrev_b32_e32 v47, 16, v165
	v_and_b32_e32 v15, 0xffff0000, v165
	v_mul_f32_e32 v42, v43, v43
	v_mul_f32_e32 v44, v45, v45
	v_pk_add_f32 v[10:11], v[36:37], v[10:11]
	v_mul_f32_e32 v110, v111, v111
	v_mul_f32_e32 v6, v7, v7
	v_lshlrev_b32_e32 v59, 16, v166
	v_and_b32_e32 v61, 0xffff0000, v166
	v_mul_f32_e32 v46, v47, v47
	v_mul_f32_e32 v14, v15, v15
	v_pk_add_f32 v[6:7], v[110:111], v[6:7]
	s_waitcnt vmcnt(8)
	v_lshlrev_b32_e32 v111, 16, v188
	v_and_b32_e32 v113, 0xffff0000, v188
	v_lshlrev_b32_e32 v115, 16, v189
	v_and_b32_e32 v117, 0xffff0000, v189
	v_pk_add_f32 v[0:1], v[12:13], v[10:11]
	v_pk_add_f32 v[10:11], v[42:43], v[44:45]
	v_lshlrev_b32_e32 v63, 16, v167
	v_and_b32_e32 v17, 0xffff0000, v167
	v_mul_f32_e32 v58, v59, v59
	v_mul_f32_e32 v60, v61, v61
	v_pk_add_f32 v[0:1], v[10:11], v[0:1]
	v_pk_add_f32 v[10:11], v[46:47], v[14:15]
	v_mul_f32_e32 v62, v63, v63
	v_mul_f32_e32 v16, v17, v17
	v_mul_f32_e32 v66, v65, v65
	v_pk_add_f32 v[0:1], v[10:11], v[0:1]
	v_pk_add_f32 v[10:11], v[58:59], v[60:61]
	v_pk_add_f32 v[38:39], v[108:109], v[66:67]
	v_pk_add_f32 v[0:1], v[10:11], v[0:1]
	v_pk_add_f32 v[10:11], v[62:63], v[16:17]
	v_pk_add_f32 v[18:19], v[38:39], v[18:19]
	v_lshlrev_b32_e32 v35, 16, v172
	v_and_b32_e32 v37, 0xffff0000, v172
	v_pk_add_f32 v[0:1], v[10:11], v[0:1]
	v_pk_add_f32 v[18:19], v[40:41], v[18:19]
	v_mul_f32_e32 v34, v35, v35
	v_mul_f32_e32 v36, v37, v37
	v_lshlrev_b32_e32 v39, 16, v173
	v_and_b32_e32 v23, 0xffff0000, v173
	ds_bpermute_b32 v11, v71, v1
	ds_bpermute_b32 v10, v71, v0
	v_mul_f32_e32 v38, v39, v39
	v_mul_f32_e32 v22, v23, v23
	v_lshlrev_b32_e32 v41, 16, v174
	v_and_b32_e32 v65, 0xffff0000, v174
	v_pk_add_f32 v[16:17], v[20:21], v[18:19]
	v_pk_add_f32 v[18:19], v[34:35], v[36:37]
	v_mul_f32_e32 v40, v41, v41
	v_mul_f32_e32 v64, v65, v65
	v_lshlrev_b32_e32 v67, 16, v175
	v_and_b32_e32 v25, 0xffff0000, v175
	v_pk_add_f32 v[16:17], v[18:19], v[16:17]
	v_pk_add_f32 v[18:19], v[38:39], v[22:23]
	v_mul_f32_e32 v66, v67, v67
	v_mul_f32_e32 v24, v25, v25
	v_pk_add_f32 v[16:17], v[18:19], v[16:17]
	v_pk_add_f32 v[18:19], v[40:41], v[64:65]
	s_waitcnt lgkmcnt(0)
	v_pk_add_f32 v[0:1], v[0:1], v[10:11]
	v_pk_add_f32 v[16:17], v[18:19], v[16:17]
	v_pk_add_f32 v[18:19], v[66:67], v[24:25]
	ds_bpermute_b32 v11, v72, v1
	v_pk_add_f32 v[16:17], v[18:19], v[16:17]
	ds_bpermute_b32 v10, v72, v0
	ds_bpermute_b32 v19, v71, v17
	ds_bpermute_b32 v18, v71, v16
	v_mul_f32_e32 v100, v101, v101
	v_mul_f32_e32 v102, v103, v103
	s_waitcnt lgkmcnt(2)
	v_pk_add_f32 v[0:1], v[0:1], v[10:11]
	ds_bpermute_b32 v11, v73, v1
	s_waitcnt lgkmcnt(1)
	v_pk_add_f32 v[16:17], v[16:17], v[18:19]
	ds_bpermute_b32 v10, v73, v0
	ds_bpermute_b32 v19, v72, v17
	ds_bpermute_b32 v18, v72, v16
	v_pk_add_f32 v[26:27], v[68:69], v[26:27]
	v_pk_add_f32 v[68:69], v[100:101], v[102:103]
	s_waitcnt lgkmcnt(2)
	v_pk_add_f32 v[0:1], v[0:1], v[10:11]
	v_pk_add_f32 v[26:27], v[68:69], v[26:27]
	s_waitcnt lgkmcnt(0)
	v_pk_add_f32 v[10:11], v[16:17], v[18:19]
	ds_bpermute_b32 v17, v73, v11
	ds_bpermute_b32 v16, v73, v10
	v_lshlrev_b32_e32 v69, 16, v29
	v_and_b32_e32 v29, 0xffff0000, v29
	v_mul_f32_e32 v68, v69, v69
	v_mul_f32_e32 v28, v29, v29
	s_waitcnt lgkmcnt(0)
	v_pk_add_f32 v[10:11], v[10:11], v[16:17]
	ds_bpermute_b32 v17, v74, v11
	ds_bpermute_b32 v16, v74, v10
	v_pk_add_f32 v[28:29], v[68:69], v[28:29]
	v_lshlrev_b32_e32 v69, 16, v180
	v_and_b32_e32 v101, 0xffff0000, v180
	v_mul_f32_e32 v68, v69, v69
	v_mul_f32_e32 v100, v101, v101
	v_lshlrev_b32_e32 v103, 16, v181
	v_and_b32_e32 v31, 0xffff0000, v181
	v_mul_f32_e32 v110, v111, v111
	v_mul_f32_e32 v112, v113, v113
	v_mul_f32_e32 v102, v103, v103
	v_mul_f32_e32 v30, v31, v31
	v_lshlrev_b32_e32 v105, 16, v182
	v_and_b32_e32 v107, 0xffff0000, v182
	v_mul_f32_e32 v114, v115, v115
	v_mul_f32_e32 v116, v117, v117
	v_lshlrev_b32_e32 v13, 16, v190
	v_and_b32_e32 v15, 0xffff0000, v190
	s_waitcnt lgkmcnt(0)
; DI float bf_lo(unsigned u) { return __uint_as_float(u << 16); }
; DI float bf_hi(unsigned u) { return __uint_as_float(u & 0xffff0000u); }
; DI void sg_phase(const Params& p, lds_t* shm) {
;     ...
;       for (int q = 0; q < 4; ++q) { const u32x4* rp = (const u32x4*)(Vs + (size_t)(w * 128 + wid * 16 + t4 + q) * DM); rv[q][0] = rp[lane]; rv[q][1] = rp[lane + 64]; }
;       float sm[4], sq[4];
; #pragma unroll
;       for (int q = 0; q < 4; ++q) { float a0 = 0.f, a1 = 0.f;
; #pragma unroll
;         for (int i = 0; i < 2; ++i)
; #pragma unroll
;           for (int e = 0; e < 4; ++e) { const float a = bf_lo(rv[q][i][e]), bb = bf_hi(rv[q][i][e]); a0 += a + bb; a1 += a * a + bb * bb; }
;         sm[q] = a0; sq[q] = a1; }
; #pragma unroll
;       for (int q = 0; q < 4; ++q) { sm[q] = wave_sum(sm[q]); sq[q] = wave_sum(sq[q]); }
; #pragma unroll
;       for (int q = 0; q < 4; ++q) { const int j = wid * 16 + t4 + q; const float mu = sm[q] * (1.0f / DM), var = fmaxf(sq[q] * (1.0f / DM) - mu * mu, 0.f);
;         if (lane == 0) { stats[2 * j] = mu; stats[2 * j + 1] = rsqrtf(var + 1e-5f); } }
	v_pk_add_f32 v[10:11], v[10:11], v[16:17]
	v_pk_add_f32 v[16:17], v[28:29], v[26:27]
	v_pk_add_f32 v[18:19], v[68:69], v[100:101]
	v_pk_add_f32 v[4:5], v[6:7], v[4:5]
	v_pk_add_f32 v[6:7], v[110:111], v[112:113]
	v_mul_f32_e32 v104, v105, v105
	v_mul_f32_e32 v106, v107, v107
	v_lshlrev_b32_e32 v109, 16, v183
	v_and_b32_e32 v33, 0xffff0000, v183
	v_mul_f32_e32 v12, v13, v13
	v_mul_f32_e32 v14, v15, v15
	v_lshlrev_b32_e32 v21, 16, v191
	v_and_b32_e32 v23, 0xffff0000, v191
	v_pk_add_f32 v[16:17], v[18:19], v[16:17]
	v_pk_add_f32 v[18:19], v[102:103], v[30:31]
	v_pk_add_f32 v[4:5], v[6:7], v[4:5]
	v_pk_add_f32 v[6:7], v[114:115], v[116:117]
	v_mul_f32_e32 v108, v109, v109
	v_mul_f32_e32 v32, v33, v33
	v_mul_f32_e32 v20, v21, v21
	v_mul_f32_e32 v22, v23, v23
	v_pk_add_f32 v[16:17], v[18:19], v[16:17]
	v_pk_add_f32 v[18:19], v[104:105], v[106:107]
	v_pk_add_f32 v[4:5], v[6:7], v[4:5]
	v_pk_add_f32 v[6:7], v[12:13], v[14:15]
	v_pk_add_f32 v[16:17], v[18:19], v[16:17]
	v_pk_add_f32 v[18:19], v[108:109], v[32:33]
	v_pk_add_f32 v[4:5], v[6:7], v[4:5]
	v_pk_add_f32 v[6:7], v[20:21], v[22:23]
	v_pk_add_f32 v[16:17], v[18:19], v[16:17]
	v_pk_add_f32 v[4:5], v[6:7], v[4:5]
	ds_bpermute_b32 v19, v71, v17
	ds_bpermute_b32 v18, v71, v16
	ds_bpermute_b32 v7, v71, v5
	ds_bpermute_b32 v6, v71, v4
	ds_bpermute_b32 v13, v75, v11
	ds_bpermute_b32 v12, v75, v10
	s_waitcnt lgkmcnt(4)
	v_pk_add_f32 v[14:15], v[16:17], v[18:19]
	ds_bpermute_b32 v17, v72, v15
	s_waitcnt lgkmcnt(3)
	v_pk_add_f32 v[4:5], v[4:5], v[6:7]
	ds_bpermute_b32 v16, v72, v14
	ds_bpermute_b32 v7, v72, v5
	ds_bpermute_b32 v6, v72, v4
	s_waitcnt lgkmcnt(4)
	v_pk_add_f32 v[12:13], v[10:11], v[12:13]
	ds_bpermute_b32 v3, v74, v1
	s_waitcnt lgkmcnt(3)
	v_pk_add_f32 v[14:15], v[14:15], v[16:17]
	ds_bpermute_b32 v17, v73, v15
	s_waitcnt lgkmcnt(2)
	v_pk_add_f32 v[4:5], v[4:5], v[6:7]
	ds_bpermute_b32 v16, v73, v14
	ds_bpermute_b32 v7, v73, v5
	ds_bpermute_b32 v6, v73, v4
	ds_bpermute_b32 v2, v74, v0
	s_waitcnt lgkmcnt(3)
	v_pk_add_f32 v[10:11], v[14:15], v[16:17]
	ds_bpermute_b32 v15, v74, v11
	s_waitcnt lgkmcnt(2)
	v_pk_add_f32 v[4:5], v[4:5], v[6:7]
	ds_bpermute_b32 v14, v74, v10
	ds_bpermute_b32 v7, v74, v5
	ds_bpermute_b32 v6, v74, v4
	s_waitcnt lgkmcnt(4)
	v_pk_add_f32 v[0:1], v[0:1], v[2:3]
	ds_bpermute_b32 v3, v75, v1
	s_waitcnt lgkmcnt(3)
	v_pk_add_f32 v[10:11], v[10:11], v[14:15]
	ds_bpermute_b32 v2, v75, v0
	s_waitcnt lgkmcnt(2)
	v_pk_add_f32 v[4:5], v[4:5], v[6:7]
	ds_bpermute_b32 v15, v75, v11
	ds_bpermute_b32 v14, v75, v10
	ds_bpermute_b32 v7, v75, v5
	ds_bpermute_b32 v6, v75, v4
	s_waitcnt lgkmcnt(4)
	v_pk_add_f32 v[0:1], v[0:1], v[2:3]
	ds_bpermute_b32 v3, v76, v1
	s_waitcnt lgkmcnt(3)
	v_pk_add_f32 v[10:11], v[10:11], v[14:15]
	ds_bpermute_b32 v2, v76, v0
	s_waitcnt lgkmcnt(2)
	v_pk_add_f32 v[4:5], v[4:5], v[6:7]
	ds_bpermute_b32 v17, v76, v13
	ds_bpermute_b32 v16, v76, v12
	ds_bpermute_b32 v15, v76, v11
	ds_bpermute_b32 v14, v76, v10
	ds_bpermute_b32 v7, v76, v5
	ds_bpermute_b32 v6, v76, v4
	s_and_saveexec_b64 s[0:1], vcc
	s_cbranch_execz .LBB0_391
	s_waitcnt lgkmcnt(6)
	v_pk_add_f32 v[0:1], v[0:1], v[2:3]
	s_waitcnt lgkmcnt(2)
	v_pk_add_f32 v[10:11], v[10:11], v[14:15]
	v_pk_mul_f32 v[18:19], v[0:1], s[10:11] op_sel_hi:[1,0]
	v_pk_mul_f32 v[10:11], v[10:11], s[10:11] op_sel_hi:[1,0]
	v_fma_f32 v0, -v19, v19, v18
	v_max_f32_e32 v0, 0, v0
	v_add_f32_e32 v0, 0x3727c5ac, v0
	v_mul_f32_e32 v1, 0x4b800000, v0
	v_cmp_gt_f32_e64 s[4:5], s2, v0
	s_waitcnt lgkmcnt(0)
	v_pk_add_f32 v[4:5], v[4:5], v[6:7]
	v_fma_f32 v9, -v11, v11, v10
	v_cndmask_b32_e64 v0, v0, v1, s[4:5]
	v_rsq_f32_e32 v2, v0
	v_pk_add_f32 v[0:1], v[12:13], v[16:17]
	v_pk_mul_f32 v[4:5], v[4:5], s[10:11] op_sel_hi:[1,0]
	v_pk_mul_f32 v[12:13], v[0:1], s[10:11] op_sel_hi:[1,0]
	v_max_f32_e32 v9, 0, v9
	v_fma_f32 v0, -v13, v13, v12
	v_max_f32_e32 v0, 0, v0
	v_add_f32_e32 v0, 0x3727c5ac, v0
	v_mul_f32_e32 v1, 0x4b800000, v0
	v_cmp_gt_f32_e64 s[6:7], s2, v0
	v_fma_f32 v4, -v5, v5, v4
	v_add_f32_e32 v9, 0x3727c5ac, v9
	v_cndmask_b32_e64 v0, v0, v1, s[6:7]
	v_rsq_f32_e32 v0, v0
	v_mul_f32_e32 v1, 0x45800000, v2
	v_max_f32_e32 v4, 0, v4
	v_cndmask_b32_e64 v1, v2, v1, s[4:5]
	v_mul_f32_e32 v2, 0x45800000, v0
	v_mul_f32_e32 v10, 0x4b800000, v9
	v_cmp_gt_f32_e64 s[4:5], s2, v9
	v_add_f32_e32 v4, 0x3727c5ac, v4
	v_cndmask_b32_e64 v3, v0, v2, s[6:7]
	v_cndmask_b32_e64 v9, v9, v10, s[4:5]
	v_mul_f32_e32 v6, 0x4b800000, v4
	v_cmp_gt_f32_e64 s[6:7], s2, v4
	v_rsq_f32_e32 v9, v9
	v_mov_b32_e32 v0, v19
	v_cndmask_b32_e64 v4, v4, v6, s[6:7]
	v_rsq_f32_e32 v4, v4
	v_mov_b32_e32 v2, v13
	ds_write_b128 v99, v[0:3] offset:32800
	v_mul_f32_e32 v0, 0x45800000, v9
	v_cndmask_b32_e64 v1, v9, v0, s[4:5]
	v_mul_f32_e32 v0, 0x45800000, v4
	v_cndmask_b32_e64 v3, v4, v0, s[6:7]
	v_mov_b32_e32 v0, v11
	v_mov_b32_e32 v2, v5
	ds_write_b128 v99, v[0:3] offset:32816
; DI float bf_lo(unsigned u) { return __uint_as_float(u << 16); }
; DI float bf_hi(unsigned u) { return __uint_as_float(u & 0xffff0000u); }
; DI void sg_phase(const Params& p, lds_t* shm) {
;     ...
;     for (int t4 = 0; t4 < 16; t4 += 4) {
;       u32x4 rv[4][2];
; #pragma unroll
;       for (int q = 0; q < 4; ++q) { const u32x4* rp = (const u32x4*)(Vs + (size_t)(w * 128 + wid * 16 + t4 + q) * DM); rv[q][0] = rp[lane]; rv[q][1] = rp[lane + 64]; }
;       float sm[4], sq[4];
; #pragma unroll
;       for (int q = 0; q < 4; ++q) { float a0 = 0.f, a1 = 0.f;
; #pragma unroll
;         for (int i = 0; i < 2; ++i)
; #pragma unroll
;           for (int e = 0; e < 4; ++e) { const float a = bf_lo(rv[q][i][e]), bb = bf_hi(rv[q][i][e]); a0 += a + bb; a1 += a * a + bb * bb; }
;         sm[q] = a0; sq[q] = a1; }
.LBB0_391:
	s_or_b64 exec, exec, s[0:1]
	v_or_b32_e32 v230, 12, v8
	v_ashrrev_i32_e32 v231, 31, v230
	v_lshlrev_b64 v[230:231], 11, v[230:231]
	v_lshl_add_u64 v[230:231], v[50:51], 0, v[230:231]
	global_load_dwordx4 v[160:163], v[230:231], off
	global_load_dwordx4 v[164:167], v[230:231], off offset:1024
	v_or_b32_e32 v230, 13, v8
	v_ashrrev_i32_e32 v231, 31, v230
	v_lshlrev_b64 v[230:231], 11, v[230:231]
	v_lshl_add_u64 v[230:231], v[50:51], 0, v[230:231]
	global_load_dwordx4 v[168:171], v[230:231], off
	global_load_dwordx4 v[172:175], v[230:231], off offset:1024
	v_or_b32_e32 v230, 14, v8
	v_ashrrev_i32_e32 v231, 31, v230
	v_lshlrev_b64 v[230:231], 11, v[230:231]
	v_lshl_add_u64 v[230:231], v[50:51], 0, v[230:231]
	global_load_dwordx4 v[176:179], v[230:231], off
	global_load_dwordx4 v[180:183], v[230:231], off offset:1024
	v_or_b32_e32 v230, 15, v8
	v_ashrrev_i32_e32 v231, 31, v230
	v_lshlrev_b64 v[230:231], 11, v[230:231]
	v_lshl_add_u64 v[230:231], v[50:51], 0, v[230:231]
	global_load_dwordx4 v[184:187], v[230:231], off
	global_load_dwordx4 v[188:191], v[230:231], off offset:1024
	s_waitcnt lgkmcnt(2)
	s_waitcnt lgkmcnt(0)
	s_nop 0
	s_waitcnt vmcnt(15)
	v_and_b32_e32 v9, 0xffff0000, v192
	v_and_b32_e32 v35, 0xffff0000, v193
	v_lshlrev_b32_e32 v11, 16, v193
	v_lshlrev_b32_e32 v10, 16, v192
	v_lshlrev_b32_e32 v41, 16, v195
	v_and_b32_e32 v13, 0xffff0000, v195
	s_waitcnt vmcnt(13)
	v_and_b32_e32 v65, 0xffff0000, v200
	v_and_b32_e32 v67, 0xffff0000, v201
	v_lshlrev_b32_e32 v69, 16, v202
	v_and_b32_e32 v101, 0xffff0000, v202
	v_lshlrev_b32_e32 v19, 16, v201
	v_mov_b32_e32 v64, v11
	v_pk_add_f32 v[106:107], v[10:11], v[8:9] op_sel:[1,0] op_sel_hi:[0,1]
	v_lshlrev_b32_e32 v37, 16, v194
	v_and_b32_e32 v39, 0xffff0000, v194
	v_lshlrev_b32_e32 v18, 16, v200
	v_lshlrev_b32_e32 v103, 16, v203
	v_and_b32_e32 v21, 0xffff0000, v203
	v_mul_f32_e32 v104, v10, v10
	v_mov_b32_e32 v105, v11
	v_mul_f32_e32 v40, v41, v41
	v_mul_f32_e32 v12, v13, v13
	v_mul_f32_e32 v68, v69, v69
	v_mul_f32_e32 v100, v101, v101
	v_mov_b32_e32 v106, v19
	v_pk_mul_f32 v[10:11], v[10:11], v[64:65] op_sel:[1,0] op_sel_hi:[0,1]
	v_mul_f32_e32 v48, v35, v35
	v_mul_f32_e32 v34, v9, v9
	v_mul_f32_e32 v108, v18, v18
	v_mov_b32_e32 v109, v19
	v_pk_add_f32 v[110:111], v[18:19], v[64:65] op_sel:[1,0] op_sel_hi:[0,1]
	v_mul_f32_e32 v102, v103, v103
	v_mul_f32_e32 v20, v21, v21
	v_pk_add_f32 v[12:13], v[40:41], v[12:13]
	v_pk_mul_f32 v[18:19], v[18:19], v[106:107] op_sel:[1,0] op_sel_hi:[0,1]
	v_pk_add_f32 v[40:41], v[68:69], v[100:101]
	v_mov_b32_e32 v11, v107
	s_waitcnt vmcnt(11)
	v_and_b32_e32 v9, 0xffff0000, v208
	v_and_b32_e32 v69, 0xffff0000, v209
	v_lshlrev_b32_e32 v27, 16, v209
	v_lshlrev_b32_e32 v26, 16, v208
	v_pk_add_f32 v[34:35], v[104:105], v[34:35]
	v_pk_add_f32 v[20:21], v[102:103], v[20:21]
	v_mov_b32_e32 v19, v111
	v_pk_add_f32 v[10:11], v[10:11], v[48:49]
	v_mul_f32_e32 v48, v67, v67
	v_lshlrev_b32_e32 v101, 16, v210
	v_and_b32_e32 v103, 0xffff0000, v210
	v_mul_f32_e32 v104, v26, v26
	v_mov_b32_e32 v28, v27
	v_mov_b32_e32 v105, v27
	v_mul_f32_e32 v68, v9, v9
	v_pk_add_f32 v[18:19], v[18:19], v[48:49]
	v_mul_f32_e32 v48, v69, v69
	v_pk_add_f32 v[68:69], v[104:105], v[68:69]
	v_mov_b32_e32 v29, v211
	v_pk_mul_f32 v[104:105], v[26:27], v[28:29] op_sel:[1,0] op_sel_hi:[0,1]
	v_pk_add_f32 v[26:27], v[26:27], v[8:9] op_sel:[1,0] op_sel_hi:[0,1]
	s_waitcnt vmcnt(9)
	v_and_b32_e32 v9, 0xffff0000, v222
	v_and_b32_e32 v111, 0xffff0000, v223
	v_lshlrev_b32_e32 v5, 16, v223
	v_lshlrev_b32_e32 v4, 16, v222
	v_mov_b32_e32 v105, v27
	v_lshlrev_b32_e32 v113, 16, v224
	v_and_b32_e32 v115, 0xffff0000, v224
	v_mul_f32_e32 v116, v4, v4
	v_mov_b32_e32 v6, v5
	v_mov_b32_e32 v117, v5
	v_mul_f32_e32 v110, v9, v9
	v_pk_add_f32 v[26:27], v[104:105], v[48:49]
	v_mul_f32_e32 v48, v111, v111
	v_pk_add_f32 v[110:111], v[116:117], v[110:111]
	v_mov_b32_e32 v7, v225
	v_pk_mul_f32 v[116:117], v[4:5], v[6:7] op_sel:[1,0] op_sel_hi:[0,1]
	v_pk_add_f32 v[4:5], v[4:5], v[8:9] op_sel:[1,0] op_sel_hi:[0,1]
	v_mov_b32_e32 v117, v5
	v_mul_f32_e32 v112, v113, v113
	v_mul_f32_e32 v114, v115, v115
	v_pk_add_f32 v[4:5], v[116:117], v[48:49]
	v_mul_f32_e32 v36, v37, v37
	v_mul_f32_e32 v38, v39, v39
	v_pk_add_f32 v[4:5], v[110:111], v[4:5]
	v_pk_add_f32 v[110:111], v[112:113], v[114:115]
	v_lshlrev_b32_e32 v43, 16, v196
	v_and_b32_e32 v45, 0xffff0000, v196
	v_pk_add_f32 v[36:37], v[36:37], v[38:39]
	v_pk_add_f32 v[10:11], v[34:35], v[10:11]
	v_pk_add_f32 v[4:5], v[110:111], v[4:5]
	v_lshlrev_b32_e32 v111, 16, v7
	v_and_b32_e32 v7, 0xffff0000, v7
	v_lshlrev_b32_e32 v47, 16, v197
	v_and_b32_e32 v15, 0xffff0000, v197
	v_mul_f32_e32 v42, v43, v43
	v_mul_f32_e32 v44, v45, v45
	v_pk_add_f32 v[10:11], v[36:37], v[10:11]
	v_mul_f32_e32 v110, v111, v111
	v_mul_f32_e32 v6, v7, v7
	v_lshlrev_b32_e32 v59, 16, v198
	v_and_b32_e32 v61, 0xffff0000, v198
	v_mul_f32_e32 v46, v47, v47
	v_mul_f32_e32 v14, v15, v15
	v_pk_add_f32 v[6:7], v[110:111], v[6:7]
	s_waitcnt vmcnt(8)
; DI float bf_lo(unsigned u) { return __uint_as_float(u << 16); }
; DI float bf_hi(unsigned u) { return __uint_as_float(u & 0xffff0000u); }
; DI void sg_phase(const Params& p, lds_t* shm) {
;     ...
;       for (int q = 0; q < 4; ++q) { const u32x4* rp = (const u32x4*)(Vs + (size_t)(w * 128 + wid * 16 + t4 + q) * DM); rv[q][0] = rp[lane]; rv[q][1] = rp[lane + 64]; }
;       float sm[4], sq[4];
; #pragma unroll
;       for (int q = 0; q < 4; ++q) { float a0 = 0.f, a1 = 0.f;
; #pragma unroll
;         for (int i = 0; i < 2; ++i)
; #pragma unroll
;           for (int e = 0; e < 4; ++e) { const float a = bf_lo(rv[q][i][e]), bb = bf_hi(rv[q][i][e]); a0 += a + bb; a1 += a * a + bb * bb; }
;         sm[q] = a0; sq[q] = a1; }
; #pragma unroll
;       for (int q = 0; q < 4; ++q) { sm[q] = wave_sum(sm[q]); sq[q] = wave_sum(sq[q]); }
	v_lshlrev_b32_e32 v111, 16, v226
	v_and_b32_e32 v113, 0xffff0000, v226
	v_lshlrev_b32_e32 v115, 16, v227
	v_and_b32_e32 v117, 0xffff0000, v227
	v_pk_add_f32 v[0:1], v[12:13], v[10:11]
	v_pk_add_f32 v[10:11], v[42:43], v[44:45]
	v_lshlrev_b32_e32 v63, 16, v199
	v_and_b32_e32 v17, 0xffff0000, v199
	v_mul_f32_e32 v58, v59, v59
	v_mul_f32_e32 v60, v61, v61
	v_pk_add_f32 v[0:1], v[10:11], v[0:1]
	v_pk_add_f32 v[10:11], v[46:47], v[14:15]
	v_mul_f32_e32 v62, v63, v63
	v_mul_f32_e32 v16, v17, v17
	v_mul_f32_e32 v66, v65, v65
	v_pk_add_f32 v[0:1], v[10:11], v[0:1]
	v_pk_add_f32 v[10:11], v[58:59], v[60:61]
	v_pk_add_f32 v[38:39], v[108:109], v[66:67]
	v_pk_add_f32 v[0:1], v[10:11], v[0:1]
	v_pk_add_f32 v[10:11], v[62:63], v[16:17]
	v_pk_add_f32 v[18:19], v[38:39], v[18:19]
	v_lshlrev_b32_e32 v35, 16, v204
	v_and_b32_e32 v37, 0xffff0000, v204
	v_pk_add_f32 v[0:1], v[10:11], v[0:1]
	v_pk_add_f32 v[18:19], v[40:41], v[18:19]
	v_mul_f32_e32 v34, v35, v35
	v_mul_f32_e32 v36, v37, v37
	v_lshlrev_b32_e32 v39, 16, v205
	v_and_b32_e32 v23, 0xffff0000, v205
	ds_bpermute_b32 v11, v71, v1
	ds_bpermute_b32 v10, v71, v0
	v_mul_f32_e32 v38, v39, v39
	v_mul_f32_e32 v22, v23, v23
	v_lshlrev_b32_e32 v41, 16, v206
	v_and_b32_e32 v65, 0xffff0000, v206
	v_pk_add_f32 v[16:17], v[20:21], v[18:19]
	v_pk_add_f32 v[18:19], v[34:35], v[36:37]
	v_mul_f32_e32 v40, v41, v41
	v_mul_f32_e32 v64, v65, v65
	v_lshlrev_b32_e32 v67, 16, v207
	v_and_b32_e32 v25, 0xffff0000, v207
	v_pk_add_f32 v[16:17], v[18:19], v[16:17]
	v_pk_add_f32 v[18:19], v[38:39], v[22:23]
	v_mul_f32_e32 v66, v67, v67
	v_mul_f32_e32 v24, v25, v25
	v_pk_add_f32 v[16:17], v[18:19], v[16:17]
	v_pk_add_f32 v[18:19], v[40:41], v[64:65]
	s_waitcnt lgkmcnt(0)
	v_pk_add_f32 v[0:1], v[0:1], v[10:11]
	v_pk_add_f32 v[16:17], v[18:19], v[16:17]
	v_pk_add_f32 v[18:19], v[66:67], v[24:25]
	ds_bpermute_b32 v11, v72, v1
	v_pk_add_f32 v[16:17], v[18:19], v[16:17]
	ds_bpermute_b32 v10, v72, v0
	ds_bpermute_b32 v19, v71, v17
	ds_bpermute_b32 v18, v71, v16
	v_mul_f32_e32 v100, v101, v101
	v_mul_f32_e32 v102, v103, v103
	s_waitcnt lgkmcnt(2)
	v_pk_add_f32 v[0:1], v[0:1], v[10:11]
	ds_bpermute_b32 v11, v73, v1
	s_waitcnt lgkmcnt(1)
	v_pk_add_f32 v[16:17], v[16:17], v[18:19]
	ds_bpermute_b32 v10, v73, v0
	ds_bpermute_b32 v19, v72, v17
	ds_bpermute_b32 v18, v72, v16
	v_pk_add_f32 v[26:27], v[68:69], v[26:27]
	v_pk_add_f32 v[68:69], v[100:101], v[102:103]
	s_waitcnt lgkmcnt(2)
	v_pk_add_f32 v[0:1], v[0:1], v[10:11]
	v_pk_add_f32 v[26:27], v[68:69], v[26:27]
	s_waitcnt lgkmcnt(0)
	v_pk_add_f32 v[10:11], v[16:17], v[18:19]
	ds_bpermute_b32 v17, v73, v11
	ds_bpermute_b32 v16, v73, v10
	v_lshlrev_b32_e32 v69, 16, v29
	v_and_b32_e32 v29, 0xffff0000, v29
	v_mul_f32_e32 v68, v69, v69
	v_mul_f32_e32 v28, v29, v29
	s_waitcnt lgkmcnt(0)
	v_pk_add_f32 v[10:11], v[10:11], v[16:17]
	ds_bpermute_b32 v17, v74, v11
	ds_bpermute_b32 v16, v74, v10
	v_pk_add_f32 v[28:29], v[68:69], v[28:29]
	v_lshlrev_b32_e32 v69, 16, v218
	v_and_b32_e32 v101, 0xffff0000, v218
	v_mul_f32_e32 v68, v69, v69
	v_mul_f32_e32 v100, v101, v101
	v_lshlrev_b32_e32 v103, 16, v219
	v_and_b32_e32 v31, 0xffff0000, v219
	v_mul_f32_e32 v110, v111, v111
	v_mul_f32_e32 v112, v113, v113
	v_mul_f32_e32 v102, v103, v103
	v_mul_f32_e32 v30, v31, v31
	v_lshlrev_b32_e32 v105, 16, v220
	v_and_b32_e32 v107, 0xffff0000, v220
	v_mul_f32_e32 v114, v115, v115
	v_mul_f32_e32 v116, v117, v117
	v_lshlrev_b32_e32 v13, 16, v228
	v_and_b32_e32 v15, 0xffff0000, v228
	s_waitcnt lgkmcnt(0)
	v_pk_add_f32 v[10:11], v[10:11], v[16:17]
	v_pk_add_f32 v[16:17], v[28:29], v[26:27]
	v_pk_add_f32 v[18:19], v[68:69], v[100:101]
	v_pk_add_f32 v[4:5], v[6:7], v[4:5]
	v_pk_add_f32 v[6:7], v[110:111], v[112:113]
	v_mul_f32_e32 v104, v105, v105
	v_mul_f32_e32 v106, v107, v107
	v_lshlrev_b32_e32 v109, 16, v221
	v_and_b32_e32 v33, 0xffff0000, v221
	v_mul_f32_e32 v12, v13, v13
	v_mul_f32_e32 v14, v15, v15
	v_lshlrev_b32_e32 v21, 16, v229
	v_and_b32_e32 v23, 0xffff0000, v229
	v_pk_add_f32 v[16:17], v[18:19], v[16:17]
	v_pk_add_f32 v[18:19], v[102:103], v[30:31]
	v_pk_add_f32 v[4:5], v[6:7], v[4:5]
	v_pk_add_f32 v[6:7], v[114:115], v[116:117]
	v_mul_f32_e32 v108, v109, v109
	v_mul_f32_e32 v32, v33, v33
	v_mul_f32_e32 v20, v21, v21
	v_mul_f32_e32 v22, v23, v23
	v_pk_add_f32 v[16:17], v[18:19], v[16:17]
	v_pk_add_f32 v[18:19], v[104:105], v[106:107]
	v_pk_add_f32 v[4:5], v[6:7], v[4:5]
	v_pk_add_f32 v[6:7], v[12:13], v[14:15]
	v_pk_add_f32 v[16:17], v[18:19], v[16:17]
	v_pk_add_f32 v[18:19], v[108:109], v[32:33]
	v_pk_add_f32 v[4:5], v[6:7], v[4:5]
	v_pk_add_f32 v[6:7], v[20:21], v[22:23]
	v_pk_add_f32 v[16:17], v[18:19], v[16:17]
	v_pk_add_f32 v[4:5], v[6:7], v[4:5]
	ds_bpermute_b32 v19, v71, v17
	ds_bpermute_b32 v18, v71, v16
	ds_bpermute_b32 v7, v71, v5
	ds_bpermute_b32 v6, v71, v4
	ds_bpermute_b32 v13, v75, v11
	ds_bpermute_b32 v12, v75, v10
	s_waitcnt lgkmcnt(4)
	v_pk_add_f32 v[14:15], v[16:17], v[18:19]
	ds_bpermute_b32 v17, v72, v15
	s_waitcnt lgkmcnt(3)
	v_pk_add_f32 v[4:5], v[4:5], v[6:7]
	ds_bpermute_b32 v16, v72, v14
	ds_bpermute_b32 v7, v72, v5
	ds_bpermute_b32 v6, v72, v4
	s_waitcnt lgkmcnt(4)
	v_pk_add_f32 v[12:13], v[10:11], v[12:13]
	ds_bpermute_b32 v3, v74, v1
	s_waitcnt lgkmcnt(3)
	v_pk_add_f32 v[14:15], v[14:15], v[16:17]
	ds_bpermute_b32 v17, v73, v15
	s_waitcnt lgkmcnt(2)
	v_pk_add_f32 v[4:5], v[4:5], v[6:7]
	ds_bpermute_b32 v16, v73, v14
	ds_bpermute_b32 v7, v73, v5
	ds_bpermute_b32 v6, v73, v4
	ds_bpermute_b32 v2, v74, v0
	s_waitcnt lgkmcnt(3)
	v_pk_add_f32 v[10:11], v[14:15], v[16:17]
	ds_bpermute_b32 v15, v74, v11
	s_waitcnt lgkmcnt(2)
	v_pk_add_f32 v[4:5], v[4:5], v[6:7]
	ds_bpermute_b32 v14, v74, v10
	ds_bpermute_b32 v7, v74, v5
	ds_bpermute_b32 v6, v74, v4
	s_waitcnt lgkmcnt(4)
	v_pk_add_f32 v[0:1], v[0:1], v[2:3]
	ds_bpermute_b32 v3, v75, v1
	s_waitcnt lgkmcnt(3)
	v_pk_add_f32 v[10:11], v[10:11], v[14:15]
	ds_bpermute_b32 v2, v75, v0
	s_waitcnt lgkmcnt(2)
	v_pk_add_f32 v[4:5], v[4:5], v[6:7]
	ds_bpermute_b32 v15, v75, v11
	ds_bpermute_b32 v14, v75, v10
	ds_bpermute_b32 v7, v75, v5
	ds_bpermute_b32 v6, v75, v4
	s_waitcnt lgkmcnt(4)
	v_pk_add_f32 v[0:1], v[0:1], v[2:3]
	ds_bpermute_b32 v3, v76, v1
	s_waitcnt lgkmcnt(3)
	v_pk_add_f32 v[10:11], v[10:11], v[14:15]
	ds_bpermute_b32 v2, v76, v0
	s_waitcnt lgkmcnt(2)
	v_pk_add_f32 v[4:5], v[4:5], v[6:7]
	ds_bpermute_b32 v17, v76, v13
	ds_bpermute_b32 v16, v76, v12
	ds_bpermute_b32 v15, v76, v11
	ds_bpermute_b32 v14, v76, v10
	ds_bpermute_b32 v7, v76, v5
	ds_bpermute_b32 v6, v76, v4
	s_and_saveexec_b64 s[0:1], vcc
	s_cbranch_execz .LBB0_393
; DI float bf_lo(unsigned u) { return __uint_as_float(u << 16); }
; DI float bf_hi(unsigned u) { return __uint_as_float(u & 0xffff0000u); }
; DI void sg_phase(const Params& p, lds_t* shm) {
;     ...
;     for (int t4 = 0; t4 < 16; t4 += 4) {
;       u32x4 rv[4][2];
; #pragma unroll
;       for (int q = 0; q < 4; ++q) { const u32x4* rp = (const u32x4*)(Vs + (size_t)(w * 128 + wid * 16 + t4 + q) * DM); rv[q][0] = rp[lane]; rv[q][1] = rp[lane + 64]; }
;       float sm[4], sq[4];
; #pragma unroll
;       for (int q = 0; q < 4; ++q) { float a0 = 0.f, a1 = 0.f;
; #pragma unroll
;         for (int i = 0; i < 2; ++i)
; #pragma unroll
;           for (int e = 0; e < 4; ++e) { const float a = bf_lo(rv[q][i][e]), bb = bf_hi(rv[q][i][e]); a0 += a + bb; a1 += a * a + bb * bb; }
;         sm[q] = a0; sq[q] = a1; }
;     ...
;       for (int q = 0; q < 4; ++q) { const int j = wid * 16 + t4 + q; const float mu = sm[q] * (1.0f / DM), var = fmaxf(sq[q] * (1.0f / DM) - mu * mu, 0.f);
;         if (lane == 0) { stats[2 * j] = mu; stats[2 * j + 1] = rsqrtf(var + 1e-5f); } }
	s_waitcnt lgkmcnt(6)
	v_pk_add_f32 v[0:1], v[0:1], v[2:3]
	s_waitcnt lgkmcnt(2)
	v_pk_add_f32 v[10:11], v[10:11], v[14:15]
	v_pk_mul_f32 v[18:19], v[0:1], s[10:11] op_sel_hi:[1,0]
	v_pk_mul_f32 v[10:11], v[10:11], s[10:11] op_sel_hi:[1,0]
	v_fma_f32 v0, -v19, v19, v18
	v_max_f32_e32 v0, 0, v0
	v_add_f32_e32 v0, 0x3727c5ac, v0
	v_mul_f32_e32 v1, 0x4b800000, v0
	v_cmp_gt_f32_e64 s[4:5], s2, v0
	s_waitcnt lgkmcnt(0)
	v_pk_add_f32 v[4:5], v[4:5], v[6:7]
	v_fma_f32 v9, -v11, v11, v10
	v_cndmask_b32_e64 v0, v0, v1, s[4:5]
	v_rsq_f32_e32 v2, v0
	v_pk_add_f32 v[0:1], v[12:13], v[16:17]
	v_pk_mul_f32 v[4:5], v[4:5], s[10:11] op_sel_hi:[1,0]
	v_pk_mul_f32 v[12:13], v[0:1], s[10:11] op_sel_hi:[1,0]
	v_max_f32_e32 v9, 0, v9
	v_fma_f32 v0, -v13, v13, v12
	v_max_f32_e32 v0, 0, v0
	v_add_f32_e32 v0, 0x3727c5ac, v0
	v_mul_f32_e32 v1, 0x4b800000, v0
	v_cmp_gt_f32_e64 s[6:7], s2, v0
	v_fma_f32 v4, -v5, v5, v4
	v_add_f32_e32 v9, 0x3727c5ac, v9
	v_cndmask_b32_e64 v0, v0, v1, s[6:7]
	v_rsq_f32_e32 v0, v0
	v_mul_f32_e32 v1, 0x45800000, v2
	v_max_f32_e32 v4, 0, v4
	v_cndmask_b32_e64 v1, v2, v1, s[4:5]
	v_mul_f32_e32 v2, 0x45800000, v0
	v_mul_f32_e32 v10, 0x4b800000, v9
	v_cmp_gt_f32_e64 s[4:5], s2, v9
	v_add_f32_e32 v4, 0x3727c5ac, v4
	v_cndmask_b32_e64 v3, v0, v2, s[6:7]
	v_cndmask_b32_e64 v9, v9, v10, s[4:5]
	v_mul_f32_e32 v6, 0x4b800000, v4
	v_cmp_gt_f32_e64 s[6:7], s2, v4
	v_rsq_f32_e32 v9, v9
	v_mov_b32_e32 v0, v19
	v_cndmask_b32_e64 v4, v4, v6, s[6:7]
	v_rsq_f32_e32 v4, v4
	v_mov_b32_e32 v2, v13
	ds_write_b128 v99, v[0:3] offset:32832
	v_mul_f32_e32 v0, 0x45800000, v9
	v_cndmask_b32_e64 v1, v9, v0, s[4:5]
	v_mul_f32_e32 v0, 0x45800000, v4
	v_cndmask_b32_e64 v3, v4, v0, s[6:7]
	v_mov_b32_e32 v0, v11
	v_mov_b32_e32 v2, v5
	ds_write_b128 v99, v[0:3] offset:32848
.LBB0_393:
	s_or_b64 exec, exec, s[0:1]
	s_waitcnt lgkmcnt(2)
	s_waitcnt lgkmcnt(0)
	s_nop 0
	s_waitcnt vmcnt(7)
	v_and_b32_e32 v35, 0xffff0000, v161
	v_lshlrev_b32_e32 v11, 16, v161
	v_and_b32_e32 v9, 0xffff0000, v160
	v_lshlrev_b32_e32 v10, 16, v160
	v_mov_b32_e32 v8, v11
	v_lshlrev_b32_e32 v37, 16, v162
	v_and_b32_e32 v39, 0xffff0000, v162
	s_waitcnt vmcnt(5)
	v_and_b32_e32 v65, 0xffff0000, v168
	v_and_b32_e32 v67, 0xffff0000, v169
	v_lshlrev_b32_e32 v69, 16, v170
	v_and_b32_e32 v101, 0xffff0000, v170
	v_lshlrev_b32_e32 v19, 16, v169
	v_lshlrev_b32_e32 v18, 16, v168
	v_mul_f32_e32 v34, v9, v9
	v_pk_add_f32 v[106:107], v[10:11], v[8:9] op_sel:[1,0] op_sel_hi:[0,1]
	v_pk_mul_f32 v[8:9], v[10:11], v[8:9] op_sel:[1,0] op_sel_hi:[0,1]
	v_lshlrev_b32_e32 v103, 16, v171
	v_and_b32_e32 v21, 0xffff0000, v171
	v_mul_f32_e32 v48, v35, v35
	v_mul_f32_e32 v36, v37, v37
	v_mul_f32_e32 v38, v39, v39
	v_mul_f32_e32 v68, v69, v69
	v_mul_f32_e32 v100, v101, v101
	v_mul_f32_e32 v108, v18, v18
	v_mov_b32_e32 v64, v19
	v_mov_b32_e32 v109, v19
	v_mul_f32_e32 v66, v65, v65
	v_mov_b32_e32 v9, v107
	v_mul_f32_e32 v104, v10, v10
	v_mov_b32_e32 v105, v11
	v_pk_add_f32 v[110:111], v[18:19], v[64:65] op_sel:[1,0] op_sel_hi:[0,1]
	v_mul_f32_e32 v102, v103, v103
	v_mul_f32_e32 v20, v21, v21
	v_pk_add_f32 v[10:11], v[36:37], v[38:39]
	v_pk_add_f32 v[36:37], v[108:109], v[66:67]
	v_pk_mul_f32 v[18:19], v[18:19], v[64:65] op_sel:[1,0] op_sel_hi:[0,1]
	v_pk_add_f32 v[38:39], v[68:69], v[100:101]
	v_pk_add_f32 v[8:9], v[8:9], v[48:49]
	v_mul_f32_e32 v48, v67, v67
	s_waitcnt vmcnt(3)
	v_and_b32_e32 v67, 0xffff0000, v176
	v_and_b32_e32 v69, 0xffff0000, v177
	v_lshlrev_b32_e32 v27, 16, v177
	v_lshlrev_b32_e32 v26, 16, v176
	v_pk_add_f32 v[34:35], v[104:105], v[34:35]
	v_pk_add_f32 v[20:21], v[102:103], v[20:21]
	v_mov_b32_e32 v19, v111
	v_lshlrev_b32_e32 v101, 16, v178
	v_and_b32_e32 v103, 0xffff0000, v178
	v_mul_f32_e32 v104, v26, v26
	v_mov_b32_e32 v28, v27
	v_mov_b32_e32 v105, v27
	v_mul_f32_e32 v68, v67, v67
	v_pk_add_f32 v[18:19], v[18:19], v[48:49]
	v_mul_f32_e32 v48, v69, v69
	v_pk_add_f32 v[68:69], v[104:105], v[68:69]
	v_mov_b32_e32 v29, v179
	v_pk_mul_f32 v[104:105], v[26:27], v[28:29] op_sel:[1,0] op_sel_hi:[0,1]
	v_pk_add_f32 v[26:27], v[26:27], v[66:67] op_sel:[1,0] op_sel_hi:[0,1]
	s_waitcnt vmcnt(1)
	v_and_b32_e32 v109, 0xffff0000, v184
	v_and_b32_e32 v111, 0xffff0000, v185
	v_lshlrev_b32_e32 v5, 16, v185
	v_lshlrev_b32_e32 v4, 16, v184
	v_mov_b32_e32 v105, v27
	v_lshlrev_b32_e32 v113, 16, v186
	v_and_b32_e32 v115, 0xffff0000, v186
	v_mul_f32_e32 v116, v4, v4
	v_mov_b32_e32 v6, v5
	v_mov_b32_e32 v117, v5
	v_mul_f32_e32 v110, v109, v109
	v_pk_add_f32 v[26:27], v[104:105], v[48:49]
	v_mul_f32_e32 v48, v111, v111
	v_pk_add_f32 v[110:111], v[116:117], v[110:111]
	v_mov_b32_e32 v7, v187
	v_pk_mul_f32 v[116:117], v[4:5], v[6:7] op_sel:[1,0] op_sel_hi:[0,1]
	v_pk_add_f32 v[4:5], v[4:5], v[108:109] op_sel:[1,0] op_sel_hi:[0,1]
	v_mov_b32_e32 v117, v5
	v_mul_f32_e32 v112, v113, v113
	v_mul_f32_e32 v114, v115, v115
	v_pk_add_f32 v[4:5], v[116:117], v[48:49]
	v_lshlrev_b32_e32 v41, 16, v163
	v_and_b32_e32 v13, 0xffff0000, v163
	v_pk_add_f32 v[4:5], v[110:111], v[4:5]
	v_pk_add_f32 v[108:109], v[112:113], v[114:115]
	v_lshlrev_b32_e32 v43, 16, v164
	v_and_b32_e32 v45, 0xffff0000, v164
	v_mul_f32_e32 v40, v41, v41
	v_mul_f32_e32 v12, v13, v13
	v_pk_add_f32 v[8:9], v[34:35], v[8:9]
	v_pk_add_f32 v[4:5], v[108:109], v[4:5]
	v_lshlrev_b32_e32 v109, 16, v7
	v_and_b32_e32 v7, 0xffff0000, v7
	v_lshlrev_b32_e32 v47, 16, v165
	v_and_b32_e32 v15, 0xffff0000, v165
	v_mul_f32_e32 v42, v43, v43
	v_mul_f32_e32 v44, v45, v45
	v_pk_add_f32 v[12:13], v[40:41], v[12:13]
	v_pk_add_f32 v[8:9], v[10:11], v[8:9]
	v_mul_f32_e32 v108, v109, v109
	v_mul_f32_e32 v6, v7, v7
	v_lshlrev_b32_e32 v59, 16, v166
	v_and_b32_e32 v61, 0xffff0000, v166
	v_mul_f32_e32 v46, v47, v47
	v_mul_f32_e32 v14, v15, v15
	v_pk_add_f32 v[6:7], v[108:109], v[6:7]
	s_waitcnt vmcnt(0)
; DI float bf_lo(unsigned u) { return __uint_as_float(u << 16); }
; DI float bf_hi(unsigned u) { return __uint_as_float(u & 0xffff0000u); }
; DI float wave_sum(float v) {
;   v += __shfl_xor(v, 32); v += __shfl_xor(v, 16); v += __shfl_xor(v, 8); v += __shfl_xor(v, 4); v += __shfl_xor(v, 2); v += __shfl_xor(v, 1); return v;
; DI void sg_phase(const Params& p, lds_t* shm) {
;     ...
;       for (int q = 0; q < 4; ++q) { const u32x4* rp = (const u32x4*)(Vs + (size_t)(w * 128 + wid * 16 + t4 + q) * DM); rv[q][0] = rp[lane]; rv[q][1] = rp[lane + 64]; }
;       float sm[4], sq[4];
; #pragma unroll
;       for (int q = 0; q < 4; ++q) { float a0 = 0.f, a1 = 0.f;
; #pragma unroll
;         for (int i = 0; i < 2; ++i)
; #pragma unroll
;           for (int e = 0; e < 4; ++e) { const float a = bf_lo(rv[q][i][e]), bb = bf_hi(rv[q][i][e]); a0 += a + bb; a1 += a * a + bb * bb; }
;         sm[q] = a0; sq[q] = a1; }
; #pragma unroll
;       for (int q = 0; q < 4; ++q) { sm[q] = wave_sum(sm[q]); sq[q] = wave_sum(sq[q]); }
	v_lshlrev_b32_e32 v109, 16, v188
	v_and_b32_e32 v111, 0xffff0000, v188
	v_lshlrev_b32_e32 v113, 16, v189
	v_and_b32_e32 v115, 0xffff0000, v189
	v_pk_add_f32 v[0:1], v[12:13], v[8:9]
	v_pk_add_f32 v[8:9], v[42:43], v[44:45]
	v_lshlrev_b32_e32 v63, 16, v167
	v_and_b32_e32 v17, 0xffff0000, v167
	v_mul_f32_e32 v58, v59, v59
	v_mul_f32_e32 v60, v61, v61
	v_pk_add_f32 v[0:1], v[8:9], v[0:1]
	v_pk_add_f32 v[8:9], v[46:47], v[14:15]
	v_mul_f32_e32 v62, v63, v63
	v_mul_f32_e32 v16, v17, v17
	v_pk_add_f32 v[0:1], v[8:9], v[0:1]
	v_pk_add_f32 v[8:9], v[58:59], v[60:61]
	v_pk_add_f32 v[10:11], v[36:37], v[18:19]
	v_pk_add_f32 v[0:1], v[8:9], v[0:1]
	v_pk_add_f32 v[8:9], v[62:63], v[16:17]
	v_lshlrev_b32_e32 v19, 16, v172
	v_and_b32_e32 v35, 0xffff0000, v172
	v_pk_add_f32 v[0:1], v[8:9], v[0:1]
	v_pk_add_f32 v[10:11], v[38:39], v[10:11]
	v_mul_f32_e32 v18, v19, v19
	v_mul_f32_e32 v34, v35, v35
	v_lshlrev_b32_e32 v37, 16, v173
	v_and_b32_e32 v23, 0xffff0000, v173
	ds_bpermute_b32 v9, v71, v1
	ds_bpermute_b32 v8, v71, v0
	v_mul_f32_e32 v36, v37, v37
	v_mul_f32_e32 v22, v23, v23
	v_lshlrev_b32_e32 v39, 16, v174
	v_and_b32_e32 v41, 0xffff0000, v174
	v_pk_add_f32 v[10:11], v[20:21], v[10:11]
	v_pk_add_f32 v[16:17], v[18:19], v[34:35]
	v_mul_f32_e32 v38, v39, v39
	v_mul_f32_e32 v40, v41, v41
	v_lshlrev_b32_e32 v65, 16, v175
	v_and_b32_e32 v25, 0xffff0000, v175
	v_pk_add_f32 v[10:11], v[16:17], v[10:11]
	v_pk_add_f32 v[16:17], v[36:37], v[22:23]
	v_mul_f32_e32 v64, v65, v65
	v_mul_f32_e32 v24, v25, v25
	v_pk_add_f32 v[10:11], v[16:17], v[10:11]
	v_pk_add_f32 v[16:17], v[38:39], v[40:41]
	s_waitcnt lgkmcnt(0)
	v_pk_add_f32 v[0:1], v[0:1], v[8:9]
	v_pk_add_f32 v[10:11], v[16:17], v[10:11]
	v_pk_add_f32 v[16:17], v[64:65], v[24:25]
	ds_bpermute_b32 v9, v72, v1
	v_pk_add_f32 v[10:11], v[16:17], v[10:11]
	ds_bpermute_b32 v8, v72, v0
	ds_bpermute_b32 v17, v71, v11
	ds_bpermute_b32 v16, v71, v10
	v_mul_f32_e32 v100, v101, v101
	v_mul_f32_e32 v102, v103, v103
	s_waitcnt lgkmcnt(2)
	v_pk_add_f32 v[0:1], v[0:1], v[8:9]
	ds_bpermute_b32 v9, v73, v1
	s_waitcnt lgkmcnt(1)
	v_pk_add_f32 v[10:11], v[10:11], v[16:17]
	ds_bpermute_b32 v8, v73, v0
	ds_bpermute_b32 v17, v72, v11
	ds_bpermute_b32 v16, v72, v10
	v_pk_add_f32 v[26:27], v[68:69], v[26:27]
	v_pk_add_f32 v[66:67], v[100:101], v[102:103]
	s_waitcnt lgkmcnt(2)
	v_pk_add_f32 v[0:1], v[0:1], v[8:9]
	v_pk_add_f32 v[26:27], v[66:67], v[26:27]
	s_waitcnt lgkmcnt(0)
	v_pk_add_f32 v[8:9], v[10:11], v[16:17]
	ds_bpermute_b32 v11, v73, v9
	ds_bpermute_b32 v10, v73, v8
	v_lshlrev_b32_e32 v67, 16, v29
	v_and_b32_e32 v29, 0xffff0000, v29
	v_mul_f32_e32 v66, v67, v67
	v_mul_f32_e32 v28, v29, v29
	s_waitcnt lgkmcnt(0)
	v_pk_add_f32 v[8:9], v[8:9], v[10:11]
	ds_bpermute_b32 v11, v74, v9
	ds_bpermute_b32 v10, v74, v8
	v_pk_add_f32 v[28:29], v[66:67], v[28:29]
	v_lshlrev_b32_e32 v67, 16, v180
	v_and_b32_e32 v69, 0xffff0000, v180
	v_mul_f32_e32 v66, v67, v67
	v_mul_f32_e32 v68, v69, v69
	v_lshlrev_b32_e32 v101, 16, v181
	v_and_b32_e32 v31, 0xffff0000, v181
	v_mul_f32_e32 v108, v109, v109
	v_mul_f32_e32 v110, v111, v111
	v_mul_f32_e32 v100, v101, v101
	v_mul_f32_e32 v30, v31, v31
	v_lshlrev_b32_e32 v103, 16, v182
	v_and_b32_e32 v105, 0xffff0000, v182
	v_mul_f32_e32 v112, v113, v113
	v_mul_f32_e32 v114, v115, v115
	v_lshlrev_b32_e32 v13, 16, v190
	v_and_b32_e32 v15, 0xffff0000, v190
	s_waitcnt lgkmcnt(0)
	v_pk_add_f32 v[8:9], v[8:9], v[10:11]
	v_pk_add_f32 v[10:11], v[28:29], v[26:27]
	v_pk_add_f32 v[16:17], v[66:67], v[68:69]
	v_pk_add_f32 v[4:5], v[6:7], v[4:5]
	v_pk_add_f32 v[6:7], v[108:109], v[110:111]
	v_mul_f32_e32 v102, v103, v103
	v_mul_f32_e32 v104, v105, v105
	v_lshlrev_b32_e32 v107, 16, v183
	v_and_b32_e32 v33, 0xffff0000, v183
	v_mul_f32_e32 v12, v13, v13
	v_mul_f32_e32 v14, v15, v15
	v_lshlrev_b32_e32 v19, 16, v191
	v_and_b32_e32 v21, 0xffff0000, v191
	v_pk_add_f32 v[10:11], v[16:17], v[10:11]
	v_pk_add_f32 v[16:17], v[100:101], v[30:31]
	v_pk_add_f32 v[4:5], v[6:7], v[4:5]
	v_pk_add_f32 v[6:7], v[112:113], v[114:115]
	v_mul_f32_e32 v106, v107, v107
	v_mul_f32_e32 v32, v33, v33
	v_mul_f32_e32 v18, v19, v19
	v_mul_f32_e32 v20, v21, v21
	v_pk_add_f32 v[10:11], v[16:17], v[10:11]
	v_pk_add_f32 v[16:17], v[102:103], v[104:105]
	v_pk_add_f32 v[4:5], v[6:7], v[4:5]
	v_pk_add_f32 v[6:7], v[12:13], v[14:15]
	v_pk_add_f32 v[10:11], v[16:17], v[10:11]
	v_pk_add_f32 v[16:17], v[106:107], v[32:33]
	v_pk_add_f32 v[4:5], v[6:7], v[4:5]
	v_pk_add_f32 v[6:7], v[18:19], v[20:21]
	v_pk_add_f32 v[10:11], v[16:17], v[10:11]
	v_pk_add_f32 v[4:5], v[6:7], v[4:5]
	ds_bpermute_b32 v17, v71, v11
	ds_bpermute_b32 v16, v71, v10
	ds_bpermute_b32 v7, v71, v5
	ds_bpermute_b32 v6, v71, v4
	ds_bpermute_b32 v13, v75, v9
	ds_bpermute_b32 v12, v75, v8
	s_waitcnt lgkmcnt(4)
	v_pk_add_f32 v[10:11], v[10:11], v[16:17]
	ds_bpermute_b32 v15, v72, v11
	s_waitcnt lgkmcnt(3)
	v_pk_add_f32 v[4:5], v[4:5], v[6:7]
	ds_bpermute_b32 v14, v72, v10
	ds_bpermute_b32 v7, v72, v5
	ds_bpermute_b32 v6, v72, v4
	ds_bpermute_b32 v3, v74, v1
	ds_bpermute_b32 v2, v74, v0
	s_waitcnt lgkmcnt(4)
	v_pk_add_f32 v[14:15], v[10:11], v[14:15]
	ds_bpermute_b32 v17, v73, v15
	s_waitcnt lgkmcnt(3)
	v_pk_add_f32 v[4:5], v[4:5], v[6:7]
	ds_bpermute_b32 v16, v73, v14
	ds_bpermute_b32 v7, v73, v5
	ds_bpermute_b32 v6, v73, v4
	v_pk_add_f32 v[10:11], v[8:9], v[12:13]
	s_waitcnt lgkmcnt(4)
	v_pk_add_f32 v[0:1], v[0:1], v[2:3]
	s_waitcnt lgkmcnt(2)
	v_pk_add_f32 v[8:9], v[14:15], v[16:17]
	ds_bpermute_b32 v13, v74, v9
	s_waitcnt lgkmcnt(1)
	v_pk_add_f32 v[4:5], v[4:5], v[6:7]
	ds_bpermute_b32 v12, v74, v8
	ds_bpermute_b32 v7, v74, v5
	ds_bpermute_b32 v6, v74, v4
	ds_bpermute_b32 v3, v75, v1
	ds_bpermute_b32 v2, v75, v0
	s_waitcnt lgkmcnt(4)
	v_pk_add_f32 v[8:9], v[8:9], v[12:13]
	ds_bpermute_b32 v13, v75, v9
	s_waitcnt lgkmcnt(3)
	v_pk_add_f32 v[4:5], v[4:5], v[6:7]
	ds_bpermute_b32 v12, v75, v8
	ds_bpermute_b32 v7, v75, v5
	ds_bpermute_b32 v6, v75, v4
	s_waitcnt lgkmcnt(4)
	v_pk_add_f32 v[0:1], v[0:1], v[2:3]
	ds_bpermute_b32 v3, v76, v1
	s_waitcnt lgkmcnt(3)
	v_pk_add_f32 v[8:9], v[8:9], v[12:13]
	ds_bpermute_b32 v2, v76, v0
	s_waitcnt lgkmcnt(2)
	v_pk_add_f32 v[4:5], v[4:5], v[6:7]
	ds_bpermute_b32 v15, v76, v11
	ds_bpermute_b32 v14, v76, v10
	ds_bpermute_b32 v13, v76, v9
	ds_bpermute_b32 v12, v76, v8
	ds_bpermute_b32 v7, v76, v5
	ds_bpermute_b32 v6, v76, v4
	s_and_saveexec_b64 s[0:1], vcc
	s_cbranch_execz .LBB0_395
; DI void sg_phase(const Params& p, lds_t* shm) {
;     ...
;       for (int q = 0; q < 4; ++q) { sm[q] = wave_sum(sm[q]); sq[q] = wave_sum(sq[q]); }
; #pragma unroll
;       for (int q = 0; q < 4; ++q) { const int j = wid * 16 + t4 + q; const float mu = sm[q] * (1.0f / DM), var = fmaxf(sq[q] * (1.0f / DM) - mu * mu, 0.f);
;         if (lane == 0) { stats[2 * j] = mu; stats[2 * j + 1] = rsqrtf(var + 1e-5f); } }
	s_waitcnt lgkmcnt(6)
	v_pk_add_f32 v[0:1], v[0:1], v[2:3]
	s_waitcnt lgkmcnt(2)
	v_pk_add_f32 v[8:9], v[8:9], v[12:13]
	v_pk_mul_f32 v[16:17], v[0:1], s[10:11] op_sel_hi:[1,0]
	v_pk_mul_f32 v[8:9], v[8:9], s[10:11] op_sel_hi:[1,0]
	v_fma_f32 v0, -v17, v17, v16
	v_max_f32_e32 v0, 0, v0
	v_add_f32_e32 v0, 0x3727c5ac, v0
	v_mul_f32_e32 v1, 0x4b800000, v0
	v_cmp_gt_f32_e64 s[4:5], s2, v0
	s_waitcnt lgkmcnt(0)
	v_pk_add_f32 v[4:5], v[4:5], v[6:7]
	v_fma_f32 v8, -v9, v9, v8
	v_cndmask_b32_e64 v0, v0, v1, s[4:5]
	v_rsq_f32_e32 v2, v0
	v_pk_add_f32 v[0:1], v[10:11], v[14:15]
	v_pk_mul_f32 v[4:5], v[4:5], s[10:11] op_sel_hi:[1,0]
	v_pk_mul_f32 v[10:11], v[0:1], s[10:11] op_sel_hi:[1,0]
	v_max_f32_e32 v8, 0, v8
	v_fma_f32 v0, -v11, v11, v10
	v_max_f32_e32 v0, 0, v0
	v_add_f32_e32 v0, 0x3727c5ac, v0
	v_mul_f32_e32 v1, 0x4b800000, v0
	v_cmp_gt_f32_e64 s[6:7], s2, v0
	v_fma_f32 v4, -v5, v5, v4
	v_add_f32_e32 v8, 0x3727c5ac, v8
	v_cndmask_b32_e64 v0, v0, v1, s[6:7]
	v_rsq_f32_e32 v0, v0
	v_mul_f32_e32 v1, 0x45800000, v2
	v_max_f32_e32 v4, 0, v4
	v_cndmask_b32_e64 v1, v2, v1, s[4:5]
	v_mul_f32_e32 v2, 0x45800000, v0
	v_mul_f32_e32 v10, 0x4b800000, v8
	v_cmp_gt_f32_e64 s[4:5], s2, v8
	v_add_f32_e32 v4, 0x3727c5ac, v4
	v_cndmask_b32_e64 v3, v0, v2, s[6:7]
	v_cndmask_b32_e64 v8, v8, v10, s[4:5]
	v_mul_f32_e32 v6, 0x4b800000, v4
	v_cmp_gt_f32_e64 s[6:7], s2, v4
	v_rsq_f32_e32 v8, v8
	v_mov_b32_e32 v0, v17
	v_cndmask_b32_e64 v4, v4, v6, s[6:7]
	v_rsq_f32_e32 v4, v4
	v_mov_b32_e32 v2, v11
	ds_write_b128 v99, v[0:3] offset:32864
	v_mul_f32_e32 v0, 0x45800000, v8
	v_cndmask_b32_e64 v1, v8, v0, s[4:5]
	v_mul_f32_e32 v0, 0x45800000, v4
	v_cndmask_b32_e64 v3, v4, v0, s[6:7]
	v_mov_b32_e32 v0, v9
	v_mov_b32_e32 v2, v5
	ds_write_b128 v99, v[0:3] offset:32880
